# v32 plus all later hand edits stacked: adaLN GEMV rewrite, cvt_pk in prologue, J gate-weight load batching, M3 V-tile load batching
# speedup vs baseline: 1.0096x; 1.0068x over previous
.LBB0_34:
	s_mul_i32 s16, s12, 0x3020000
	s_mul_hi_i32 s15, s12, 0x3020000
	s_waitcnt lgkmcnt(0)
	s_add_u32 s17, s8, s16
	s_sext_i32_i16 s13, s13
	s_addc_u32 s30, s9, s15
	s_ashr_i32 s15, s14, 31
	s_lshl_b32 s16, s13, 6
	s_lshl_b64 s[14:15], s[14:15], 2
	s_add_u32 s14, s17, s14
	s_addc_u32 s15, s30, s15
	v_add_u32_e32 v9, s16, v10
	v_lshl_add_u64 v[58:59], s[14:15], 0, v[2:3]
	v_mad_i64_i32 v[38:39], s[14:15], v9, s28, v[58:59]
	v_add_u32_e32 v30, 8, v9
	v_mad_i64_i32 v[40:41], s[14:15], v30, s28, v[58:59]
	global_load_dwordx4 v[30:33], v[38:39], off
	global_load_dwordx4 v[34:37], v[40:41], off
	v_add_u32_e32 v38, 16, v9
	v_mad_i64_i32 v[46:47], s[14:15], v38, s28, v[58:59]
	v_add_u32_e32 v38, 24, v9
	v_mad_i64_i32 v[48:49], s[14:15], v38, s28, v[58:59]
	global_load_dwordx4 v[38:41], v[46:47], off
	global_load_dwordx4 v[42:45], v[48:49], off
	v_add_u32_e32 v46, 32, v9
	v_mad_i64_i32 v[54:55], s[14:15], v46, s28, v[58:59]
	v_add_u32_e32 v46, 40, v9
	v_mad_i64_i32 v[56:57], s[14:15], v46, s28, v[58:59]
	global_load_dwordx4 v[46:49], v[54:55], off
	global_load_dwordx4 v[50:53], v[56:57], off
	v_add_u32_e32 v54, 48, v9
	v_mad_i64_i32 v[54:55], s[14:15], v54, s28, v[58:59]
	global_load_dwordx4 v[54:57], v[54:55], off
	v_add_u32_e32 v9, 56, v9
	v_mad_i64_i32 v[58:59], s[14:15], v9, s28, v[58:59]
	global_load_dwordx4 v[58:61], v[58:59], off
	s_mul_hi_i32 s13, s12, 0x1800000
	s_mul_i32 s12, s12, 0x1800000
	s_ashr_i32 s17, s16, 31
	v_lshl_add_u64 v[62:63], v[6:7], 0, s[12:13]
	s_lshl_b64 s[12:13], s[16:17], 1
	v_mov_b32_e32 v9, v3
	v_lshl_add_u64 v[62:63], v[62:63], 0, s[12:13]
	v_lshl_add_u64 v[62:63], v[62:63], 0, v[8:9]
	s_waitcnt vmcnt(7)
	ds_write2_b32 v15, v30, v31 offset1:1
	ds_write2_b32 v15, v32, v33 offset0:2 offset1:3
	s_waitcnt vmcnt(6)
	ds_write2_b32 v16, v34, v35 offset1:1
	ds_write2_b32 v17, v36, v37 offset1:1
	s_waitcnt vmcnt(5)
	ds_write2_b32 v18, v38, v39 offset1:1
	ds_write2_b32 v19, v40, v41 offset1:1
	s_waitcnt vmcnt(4)
	ds_write2_b32 v20, v42, v43 offset1:1
	ds_write2_b32 v21, v44, v45 offset1:1
	s_waitcnt vmcnt(3)
	ds_write2_b32 v22, v46, v47 offset1:1
	ds_write2_b32 v23, v48, v49 offset1:1
	s_waitcnt vmcnt(2)
	ds_write2_b32 v24, v50, v51 offset1:1
	ds_write2_b32 v25, v52, v53 offset1:1
	s_waitcnt vmcnt(1)
	ds_write2_b32 v26, v54, v55 offset1:1
	ds_write2_b32 v27, v56, v57 offset1:1
	s_waitcnt vmcnt(0)
	ds_write2_b32 v28, v58, v59 offset1:1
	ds_write2_b32 v29, v60, v61 offset1:1
	s_waitcnt lgkmcnt(0)
	ds_read2_b32 v[34:35], v14 offset0:33 offset1:41
	ds_read2_b32 v[36:37], v14 offset1:8
	ds_read2_b32 v[38:39], v14 offset0:66 offset1:74
	ds_read2_b32 v[40:41], v14 offset0:99 offset1:107
	ds_read2_b32 v[42:43], v14 offset0:132 offset1:140
	ds_read2_b32 v[44:45], v14 offset0:165 offset1:173
	ds_read2_b32 v[46:47], v14 offset0:198 offset1:206
	ds_read2_b32 v[48:49], v14 offset0:231 offset1:239
	s_waitcnt lgkmcnt(7)
	s_waitcnt lgkmcnt(6)
	s_waitcnt lgkmcnt(2)
	s_waitcnt lgkmcnt(1)
	v_add_u32_e32 v50, s6, v10
	s_waitcnt lgkmcnt(0)
	v_ashrrev_i32_e32 v51, 31, v50
	v_lshlrev_b64 v[50:51], 12, v[50:51]
	v_cvt_pk_bf16_f32 v30, v36, v34
	v_cvt_pk_bf16_f32 v31, v38, v40
	v_cvt_pk_bf16_f32 v32, v42, v44
	v_cvt_pk_bf16_f32 v33, v46, v48
	v_lshl_add_u64 v[50:51], v[62:63], 0, v[50:51]
	global_store_dwordx4 v[50:51], v[30:33], off
	s_nop 1
	v_cvt_pk_bf16_f32 v30, v37, v35
	v_cvt_pk_bf16_f32 v31, v39, v41
	v_cvt_pk_bf16_f32 v32, v43, v45
	v_add_u32_e32 v34, s6, v11
	v_ashrrev_i32_e32 v35, 31, v34
	v_lshlrev_b64 v[34:35], 12, v[34:35]
	v_cvt_pk_bf16_f32 v33, v47, v49
	ds_read2_b32 v[36:37], v14 offset0:16 offset1:24
	v_lshl_add_u64 v[34:35], v[62:63], 0, v[34:35]
	global_store_dwordx4 v[34:35], v[30:33], off
	s_nop 1
	ds_read2_b32 v[34:35], v14 offset0:49 offset1:57
	ds_read2_b32 v[38:39], v14 offset0:82 offset1:90
	ds_read2_b32 v[40:41], v14 offset0:115 offset1:123
	s_waitcnt lgkmcnt(3)
	s_waitcnt lgkmcnt(2)
	ds_read2_b32 v[42:43], v14 offset0:148 offset1:156
	ds_read2_b32 v[44:45], v14 offset0:181 offset1:189
	v_cvt_pk_bf16_f32 v30, v36, v34
	s_waitcnt lgkmcnt(3)
	s_waitcnt lgkmcnt(2)
	ds_read2_b32 v[46:47], v14 offset0:214 offset1:222
	ds_read2_b32 v[48:49], v14 offset0:247 offset1:255
	v_cvt_pk_bf16_f32 v31, v38, v40
	s_waitcnt lgkmcnt(3)
	s_waitcnt lgkmcnt(2)
	v_cvt_pk_bf16_f32 v32, v42, v44
	s_waitcnt lgkmcnt(1)
	v_add_u32_e32 v50, s6, v12
	s_waitcnt lgkmcnt(0)
	v_ashrrev_i32_e32 v51, 31, v50
	v_lshlrev_b64 v[50:51], 12, v[50:51]
	v_cvt_pk_bf16_f32 v33, v46, v48
	v_lshl_add_u64 v[50:51], v[62:63], 0, v[50:51]
	global_store_dwordx4 v[50:51], v[30:33], off
	s_nop 1
	v_cvt_pk_bf16_f32 v30, v37, v35
	v_cvt_pk_bf16_f32 v31, v39, v41
	v_cvt_pk_bf16_f32 v32, v43, v45
	v_add_u32_e32 v34, s6, v13
	v_ashrrev_i32_e32 v35, 31, v34
	v_lshlrev_b64 v[34:35], 12, v[34:35]
	v_cvt_pk_bf16_f32 v33, v47, v49
	v_lshl_add_u64 v[34:35], v[62:63], 0, v[34:35]
	global_store_dwordx4 v[34:35], v[30:33], off
	s_waitcnt lgkmcnt(0)

.LBB0_36:
	s_mul_hi_i32 s6, s29, 0x5397829d
	s_lshr_b32 s12, s6, 31
	s_ashr_i32 s6, s6, 13
	s_add_i32 s12, s6, s12
	s_mul_i32 s6, s12, 0xffff9e00
	s_add_i32 s16, s29, s6
	s_cmpk_gt_i32 s16, 0x17ff
	s_mov_b64 s[14:15], -1
	s_cbranch_scc0 .LBB0_38
	s_and_b32 s6, s16, 0x1fc0
	s_ashr_i32 s13, s12, 31
	s_addk_i32 s6, 0xe800
	s_lshl_b64 s[14:15], s[12:13], 24
	s_waitcnt lgkmcnt(0)
	s_add_u32 s17, s10, s14
	s_addc_u32 s31, s11, s15
	s_lshl_b64 s[14:15], s[12:13], 23
	s_and_b32 s13, s3, 0x7e0
	s_lshl_b32 s30, s13, 2
	v_add_u32_e32 v30, s6, v10
	s_add_u32 s30, s17, s30
	s_addc_u32 s31, s31, 0
	v_ashrrev_i32_e32 v31, 31, v30
	v_lshl_add_u64 v[32:33], s[30:31], 0, v[2:3]
	v_lshlrev_b64 v[30:31], 13, v[30:31]
	v_lshl_add_u64 v[58:59], v[32:33], 0, v[30:31]
	v_add_co_u32_e32 v38, vcc, s19, v58
	v_lshl_add_u64 v[62:63], v[4:5], 0, s[14:15]
	s_nop 0
	v_addc_co_u32_e32 v39, vcc, 0, v59, vcc
	v_add_co_u32_e32 v46, vcc, s20, v58
	global_load_dwordx4 v[30:33], v[58:59], off
	global_load_dwordx4 v[34:37], v[38:39], off
	v_addc_co_u32_e32 v47, vcc, 0, v59, vcc
	v_add_co_u32_e32 v48, vcc, s21, v58
	s_lshl_b64 s[14:15], s[6:7], 1
	s_nop 0
	v_addc_co_u32_e32 v49, vcc, 0, v59, vcc
	v_add_co_u32_e32 v54, vcc, s22, v58
	global_load_dwordx4 v[38:41], v[46:47], off
	global_load_dwordx4 v[42:45], v[48:49], off
	v_addc_co_u32_e32 v55, vcc, 0, v59, vcc
	v_add_co_u32_e32 v56, vcc, s23, v58
	v_mov_b32_e32 v9, v3
	s_nop 0
	v_addc_co_u32_e32 v57, vcc, 0, v59, vcc
	global_load_dwordx4 v[46:49], v[54:55], off
	global_load_dwordx4 v[50:53], v[56:57], off
	v_add_co_u32_e32 v54, vcc, s24, v58
	v_lshl_add_u64 v[62:63], v[62:63], 0, s[14:15]
	s_nop 0
	v_addc_co_u32_e32 v55, vcc, 0, v59, vcc
	global_load_dwordx4 v[54:57], v[54:55], off
	v_add_co_u32_e32 v58, vcc, s25, v58
	v_lshl_add_u64 v[62:63], v[62:63], 0, v[8:9]
	s_nop 0
	v_addc_co_u32_e32 v59, vcc, 0, v59, vcc
	global_load_dwordx4 v[58:61], v[58:59], off
	s_waitcnt vmcnt(7)
	ds_write2_b32 v15, v30, v31 offset1:1
	ds_write2_b32 v15, v32, v33 offset0:2 offset1:3
	s_waitcnt vmcnt(6)
	ds_write2_b32 v16, v34, v35 offset1:1
	ds_write2_b32 v17, v36, v37 offset1:1
	s_waitcnt vmcnt(5)
	ds_write2_b32 v18, v38, v39 offset1:1
	ds_write2_b32 v19, v40, v41 offset1:1
	s_waitcnt vmcnt(4)
	ds_write2_b32 v20, v42, v43 offset1:1
	ds_write2_b32 v21, v44, v45 offset1:1
	s_waitcnt vmcnt(3)
	ds_write2_b32 v22, v46, v47 offset1:1
	ds_write2_b32 v23, v48, v49 offset1:1
	s_waitcnt vmcnt(2)
	ds_write2_b32 v24, v50, v51 offset1:1
	ds_write2_b32 v25, v52, v53 offset1:1
	s_waitcnt vmcnt(1)
	ds_write2_b32 v26, v54, v55 offset1:1
	ds_write2_b32 v27, v56, v57 offset1:1
	s_waitcnt vmcnt(0)
	ds_write2_b32 v28, v58, v59 offset1:1
	ds_write2_b32 v29, v60, v61 offset1:1
	s_waitcnt lgkmcnt(0)
	ds_read2_b32 v[34:35], v14 offset0:33 offset1:41
	ds_read2_b32 v[36:37], v14 offset1:8
	ds_read2_b32 v[38:39], v14 offset0:66 offset1:74
	ds_read2_b32 v[40:41], v14 offset0:99 offset1:107
	ds_read2_b32 v[42:43], v14 offset0:132 offset1:140
	ds_read2_b32 v[44:45], v14 offset0:165 offset1:173
	ds_read2_b32 v[46:47], v14 offset0:198 offset1:206
	ds_read2_b32 v[48:49], v14 offset0:231 offset1:239
	s_waitcnt lgkmcnt(6)
	s_waitcnt lgkmcnt(5)
	s_waitcnt lgkmcnt(3)
	s_waitcnt lgkmcnt(2)
	s_waitcnt lgkmcnt(1)
	v_add_u32_e32 v50, s13, v10
	v_cvt_pk_bf16_f32 v30, v36, v34
	v_cvt_pk_bf16_f32 v31, v38, v40
	v_cvt_pk_bf16_f32 v32, v42, v44
	s_waitcnt lgkmcnt(0)
	v_ashrrev_i32_e32 v51, 31, v50
	v_lshlrev_b64 v[50:51], 12, v[50:51]
	v_cvt_pk_bf16_f32 v33, v46, v48
	v_lshl_add_u64 v[50:51], v[62:63], 0, v[50:51]
	global_store_dwordx4 v[50:51], v[30:33], off
	s_nop 1
	v_cvt_pk_bf16_f32 v30, v37, v35
	v_cvt_pk_bf16_f32 v31, v39, v41
	v_cvt_pk_bf16_f32 v32, v43, v45
	v_add_u32_e32 v34, s13, v11
	v_ashrrev_i32_e32 v35, 31, v34
	v_lshlrev_b64 v[34:35], 12, v[34:35]
	v_cvt_pk_bf16_f32 v33, v47, v49
	ds_read2_b32 v[36:37], v14 offset0:16 offset1:24
	v_lshl_add_u64 v[34:35], v[62:63], 0, v[34:35]
	global_store_dwordx4 v[34:35], v[30:33], off
	s_nop 1
	ds_read2_b32 v[34:35], v14 offset0:49 offset1:57
	ds_read2_b32 v[38:39], v14 offset0:82 offset1:90
	ds_read2_b32 v[40:41], v14 offset0:115 offset1:123
	s_waitcnt lgkmcnt(3)
	s_waitcnt lgkmcnt(2)
	ds_read2_b32 v[42:43], v14 offset0:148 offset1:156
	ds_read2_b32 v[44:45], v14 offset0:181 offset1:189
	v_cvt_pk_bf16_f32 v30, v36, v34
	s_waitcnt lgkmcnt(3)
	s_waitcnt lgkmcnt(2)
	ds_read2_b32 v[46:47], v14 offset0:214 offset1:222
	ds_read2_b32 v[48:49], v14 offset0:247 offset1:255
	v_cvt_pk_bf16_f32 v31, v38, v40
	s_waitcnt lgkmcnt(3)
	s_waitcnt lgkmcnt(2)
	v_cvt_pk_bf16_f32 v32, v42, v44
	s_waitcnt lgkmcnt(1)
	v_add_u32_e32 v50, s13, v12
	s_waitcnt lgkmcnt(0)
	v_ashrrev_i32_e32 v51, 31, v50
	v_lshlrev_b64 v[50:51], 12, v[50:51]
	v_cvt_pk_bf16_f32 v33, v46, v48
	v_lshl_add_u64 v[50:51], v[62:63], 0, v[50:51]
	global_store_dwordx4 v[50:51], v[30:33], off
	s_nop 1
	v_cvt_pk_bf16_f32 v30, v37, v35
	v_cvt_pk_bf16_f32 v31, v39, v41
	v_cvt_pk_bf16_f32 v32, v43, v45
	v_add_u32_e32 v34, s13, v13
	v_ashrrev_i32_e32 v35, 31, v34
	s_nop 0
	s_nop 0
	v_lshlrev_b64 v[34:35], 12, v[34:35]
	v_cvt_pk_bf16_f32 v33, v47, v49
	v_lshl_add_u64 v[34:35], v[62:63], 0, v[34:35]
	global_store_dwordx4 v[34:35], v[30:33], off
	s_waitcnt lgkmcnt(0)
	s_cbranch_execnz .LBB0_35
	s_branch .LBB0_39

.LBB0_80:
	s_add_i32 s8, s72, s40
	s_cmpk_lt_i32 s8, 0x2000
	s_cselect_b32 s48, s8, s40
	v_add_co_u32_e32 v2, vcc, 0xfffff000, v58
	s_ashr_i32 s49, s48, 31
	s_waitcnt lgkmcnt(0)
	v_addc_co_u32_e32 v3, vcc, -1, v59, vcc
	s_lshl_b64 s[8:9], s[48:49], 13
	global_load_dwordx4 v[64:67], v[2:3], off offset:-3072
	global_load_dwordx4 v[68:71], v[2:3], off offset:-2048
	global_load_dwordx4 v[78:81], v[2:3], off offset:-1024
	global_load_dwordx4 v[50:53], v[58:59], off offset:-4096
	global_load_dwordx4 v[46:49], v[58:59], off offset:-3072
	global_load_dwordx4 v[42:45], v[58:59], off offset:-2048
	global_load_dwordx4 v[38:41], v[58:59], off offset:-1024
	global_load_dwordx4 v[34:37], v[58:59], off
	v_lshl_add_u64 v[2:3], v[56:57], 0, s[8:9]
	global_load_dwordx4 v[30:33], v[2:3], off
	global_load_dwordx4 v[26:29], v[2:3], off offset:1024
	global_load_dwordx4 v[22:25], v[2:3], off offset:2048
	global_load_dwordx4 v[18:21], v[2:3], off offset:3072
	v_add_co_u32_e32 v2, vcc, s62, v2
	v_mov_b32_e32 v60, v84
	s_nop 0
	v_addc_co_u32_e32 v3, vcc, 0, v3, vcc
	global_load_dwordx4 v[14:17], v[2:3], off
	global_load_dwordx4 v[10:13], v[2:3], off offset:1024
	global_load_dwordx4 v[6:9], v[2:3], off offset:2048
	s_nop 0
	global_load_dwordx4 v[2:5], v[2:3], off offset:3072
	s_ashr_i32 s41, s40, 31
	v_lshlrev_b32_e32 v62, 2, v60
	v_ashrrev_i32_e32 v63, 31, v62
	v_lshlrev_b64 v[72:73], 2, v[62:63]
	v_lshl_add_u64 v[82:83], s[28:29], 0, v[72:73]
	global_load_dwordx4 v[94:97], v[82:83], off
	v_lshl_add_u64 v[76:77], s[24:25], 0, v[72:73]
	global_load_dwordx4 v[98:101], v[76:77], off
	s_add_u32 s8, s26, s34
	s_addc_u32 s9, s27, s35
	v_lshl_add_u64 v[62:63], v[62:63], 1, s[8:9]
	v_add_co_u32_e32 v74, vcc, s65, v62
	s_lshl_b64 s[8:9], s[48:49], 12
	s_nop 0
	v_addc_co_u32_e32 v75, vcc, 0, v63, vcc
	s_add_u32 s8, s3, s8
	s_addc_u32 s9, s43, s9
	v_cmp_lt_i32_e64 s[14:15], v90, v86
	s_waitcnt vmcnt(1)
	v_pk_add_f32 v[62:63], v[96:97], 1.0 op_sel_hi:[1,0]
	v_pk_add_f32 v[72:73], v[94:95], 1.0 op_sel_hi:[1,0]
	s_waitcnt vmcnt(0)
	v_pk_fma_f32 v[62:63], v[66:67], v[62:63], v[100:101]
	v_pk_fma_f32 v[64:65], v[64:65], v[72:73], v[98:99]
	v_cvt_pk_bf16_f32 v66, v64, v65
	v_cvt_pk_bf16_f32 v67, v62, v63
	global_store_dwordx2 v[74:75], v[66:67], off
	global_load_dwordx4 v[94:97], v[82:83], off offset:1024
	global_load_dwordx4 v[98:101], v[76:77], off offset:1024
	s_waitcnt vmcnt(1)
	v_pk_add_f32 v[66:67], v[96:97], 1.0 op_sel_hi:[1,0]
	v_pk_add_f32 v[72:73], v[94:95], 1.0 op_sel_hi:[1,0]
	s_waitcnt vmcnt(0)
	v_pk_fma_f32 v[66:67], v[70:71], v[66:67], v[100:101]
	v_pk_fma_f32 v[68:69], v[68:69], v[72:73], v[98:99]
	v_cvt_pk_bf16_f32 v70, v68, v69
	v_cvt_pk_bf16_f32 v71, v66, v67
	global_store_dwordx2 v[74:75], v[70:71], off offset:512
	global_load_dwordx4 v[70:73], v[82:83], off offset:2048
	s_nop 0
	global_load_dwordx4 v[94:97], v[76:77], off offset:2048
	s_waitcnt vmcnt(1)
	v_pk_add_f32 v[72:73], v[72:73], 1.0 op_sel_hi:[1,0]
	v_pk_add_f32 v[98:99], v[70:71], 1.0 op_sel_hi:[1,0]
	s_waitcnt vmcnt(0)
	v_pk_fma_f32 v[70:71], v[80:81], v[72:73], v[96:97]
	v_pk_fma_f32 v[72:73], v[78:79], v[98:99], v[94:95]
	v_cvt_pk_bf16_f32 v78, v72, v73
	v_cvt_pk_bf16_f32 v79, v70, v71
	global_store_dwordx2 v[74:75], v[78:79], off offset:1024
	global_load_dwordx4 v[78:81], v[82:83], off offset:3072
	s_nop 0
	global_load_dwordx4 v[94:97], v[76:77], off offset:3072
	v_add_co_u32_e32 v98, vcc, s62, v82
	s_waitcnt vmcnt(1)
	v_pk_add_f32 v[80:81], v[80:81], 1.0 op_sel_hi:[1,0]
	v_pk_add_f32 v[78:79], v[78:79], 1.0 op_sel_hi:[1,0]
	s_waitcnt vmcnt(0)
	v_pk_fma_f32 v[52:53], v[52:53], v[80:81], v[96:97]
	v_pk_fma_f32 v[50:51], v[50:51], v[78:79], v[94:95]
	v_addc_co_u32_e32 v99, vcc, 0, v83, vcc
	v_cvt_pk_bf16_f32 v78, v50, v51
	v_cvt_pk_bf16_f32 v79, v52, v53
	global_store_dwordx2 v[74:75], v[78:79], off offset:1536
	v_add_co_u32_e32 v100, vcc, s62, v76
	global_load_dwordx4 v[78:81], v[98:99], off
	s_nop 0
	v_addc_co_u32_e32 v101, vcc, 0, v77, vcc
	global_load_dwordx4 v[94:97], v[100:101], off
	s_waitcnt vmcnt(1)
	v_pk_add_f32 v[76:77], v[80:81], 1.0 op_sel_hi:[1,0]
	v_pk_add_f32 v[78:79], v[78:79], 1.0 op_sel_hi:[1,0]
	s_waitcnt vmcnt(0)
	v_pk_fma_f32 v[48:49], v[48:49], v[76:77], v[96:97]
	v_pk_fma_f32 v[46:47], v[46:47], v[78:79], v[94:95]
	v_cvt_pk_bf16_f32 v76, v46, v47
	v_cvt_pk_bf16_f32 v77, v48, v49
	global_store_dwordx2 v[74:75], v[76:77], off offset:2048
	global_load_dwordx4 v[76:79], v[98:99], off offset:1024
	s_nop 0
	global_load_dwordx4 v[80:83], v[100:101], off offset:1024
	s_waitcnt vmcnt(1)
	v_pk_add_f32 v[78:79], v[78:79], 1.0 op_sel_hi:[1,0]
	v_pk_add_f32 v[76:77], v[76:77], 1.0 op_sel_hi:[1,0]
	s_waitcnt vmcnt(0)
	v_pk_fma_f32 v[44:45], v[44:45], v[78:79], v[82:83]
	v_pk_fma_f32 v[42:43], v[42:43], v[76:77], v[80:81]
	v_cvt_pk_bf16_f32 v76, v42, v43
	v_cvt_pk_bf16_f32 v77, v44, v45
	global_store_dwordx2 v[74:75], v[76:77], off offset:2560
	global_load_dwordx4 v[76:79], v[98:99], off offset:2048
	s_nop 0
	global_load_dwordx4 v[80:83], v[100:101], off offset:2048
	s_waitcnt vmcnt(1)
	v_pk_add_f32 v[78:79], v[78:79], 1.0 op_sel_hi:[1,0]
	v_pk_add_f32 v[76:77], v[76:77], 1.0 op_sel_hi:[1,0]
	s_waitcnt vmcnt(0)
	v_pk_fma_f32 v[40:41], v[40:41], v[78:79], v[82:83]
	v_pk_fma_f32 v[38:39], v[38:39], v[76:77], v[80:81]
	v_cvt_pk_bf16_f32 v76, v38, v39
	v_cvt_pk_bf16_f32 v77, v40, v41
	global_store_dwordx2 v[74:75], v[76:77], off offset:3072
	global_load_dwordx4 v[76:79], v[98:99], off offset:3072
	s_nop 0
	global_load_dwordx4 v[80:83], v[100:101], off offset:3072
	s_waitcnt vmcnt(1)
	v_pk_add_f32 v[78:79], v[78:79], 1.0 op_sel_hi:[1,0]
	v_pk_add_f32 v[76:77], v[76:77], 1.0 op_sel_hi:[1,0]
	s_waitcnt vmcnt(0)
	v_pk_fma_f32 v[36:37], v[36:37], v[78:79], v[82:83]
	v_pk_fma_f32 v[34:35], v[34:35], v[76:77], v[80:81]
	v_cvt_pk_bf16_f32 v76, v34, v35
	v_cvt_pk_bf16_f32 v77, v36, v37
	global_store_dwordx2 v[74:75], v[76:77], off offset:3584
	s_nop 0
	v_lshlrev_b32_e32 v80, 2, v60
	v_ashrrev_i32_e32 v81, 31, v80
	v_lshlrev_b64 v[74:75], 2, v[80:81]
	v_lshl_add_u64 v[98:99], s[28:29], 0, v[74:75]
	global_load_dwordx4 v[76:79], v[98:99], off
	v_lshl_add_u64 v[74:75], s[24:25], 0, v[74:75]
	global_load_dwordx4 v[94:97], v[74:75], off
	v_lshl_add_u64 v[82:83], v[80:81], 1, s[8:9]
	s_waitcnt vmcnt(1)
	v_pk_add_f32 v[78:79], v[78:79], 1.0 op_sel_hi:[1,0]
	v_pk_add_f32 v[76:77], v[76:77], 1.0 op_sel_hi:[1,0]
	s_waitcnt vmcnt(0)
	v_pk_fma_f32 v[32:33], v[32:33], v[78:79], v[96:97]
	v_pk_fma_f32 v[30:31], v[30:31], v[76:77], v[94:95]
	v_cvt_pk_bf16_f32 v76, v30, v31
	v_cvt_pk_bf16_f32 v77, v32, v33
	global_store_dwordx2 v[82:83], v[76:77], off
	global_load_dwordx4 v[76:79], v[98:99], off offset:1024
	s_nop 0
	global_load_dwordx4 v[94:97], v[74:75], off offset:1024
	s_waitcnt vmcnt(1)
	v_pk_add_f32 v[78:79], v[78:79], 1.0 op_sel_hi:[1,0]
	v_pk_add_f32 v[76:77], v[76:77], 1.0 op_sel_hi:[1,0]
	s_waitcnt vmcnt(0)
	v_pk_fma_f32 v[28:29], v[28:29], v[78:79], v[96:97]
	v_pk_fma_f32 v[26:27], v[26:27], v[76:77], v[94:95]
	v_cvt_pk_bf16_f32 v76, v26, v27
	v_cvt_pk_bf16_f32 v77, v28, v29
	global_store_dwordx2 v[82:83], v[76:77], off offset:512
	global_load_dwordx4 v[76:79], v[98:99], off offset:2048
	s_nop 0
	global_load_dwordx4 v[94:97], v[74:75], off offset:2048
	s_waitcnt vmcnt(1)
	v_pk_add_f32 v[78:79], v[78:79], 1.0 op_sel_hi:[1,0]
	v_pk_add_f32 v[76:77], v[76:77], 1.0 op_sel_hi:[1,0]
	s_waitcnt vmcnt(0)
	v_pk_fma_f32 v[24:25], v[24:25], v[78:79], v[96:97]
	v_pk_fma_f32 v[22:23], v[22:23], v[76:77], v[94:95]
	v_cvt_pk_bf16_f32 v76, v22, v23
	v_cvt_pk_bf16_f32 v77, v24, v25
	global_store_dwordx2 v[82:83], v[76:77], off offset:1024
	global_load_dwordx4 v[76:79], v[98:99], off offset:3072
	s_nop 0
	global_load_dwordx4 v[94:97], v[74:75], off offset:3072
	v_add_co_u32_e32 v98, vcc, s62, v98
	s_waitcnt vmcnt(1)
	v_pk_add_f32 v[78:79], v[78:79], 1.0 op_sel_hi:[1,0]
	v_pk_add_f32 v[76:77], v[76:77], 1.0 op_sel_hi:[1,0]
	s_waitcnt vmcnt(0)
	v_pk_fma_f32 v[20:21], v[20:21], v[78:79], v[96:97]
	v_pk_fma_f32 v[18:19], v[18:19], v[76:77], v[94:95]
	v_addc_co_u32_e32 v99, vcc, 0, v99, vcc
	v_cvt_pk_bf16_f32 v76, v18, v19
	v_cvt_pk_bf16_f32 v77, v20, v21
	global_store_dwordx2 v[82:83], v[76:77], off offset:1536
	v_add_co_u32_e32 v100, vcc, s62, v74
	global_load_dwordx4 v[76:79], v[98:99], off
	s_nop 0
	v_addc_co_u32_e32 v101, vcc, 0, v75, vcc
	global_load_dwordx4 v[94:97], v[100:101], off
	v_cmp_lt_i32_e32 vcc, v85, v86
	s_waitcnt vmcnt(1)
	v_pk_add_f32 v[74:75], v[78:79], 1.0 op_sel_hi:[1,0]
	v_pk_add_f32 v[76:77], v[76:77], 1.0 op_sel_hi:[1,0]
	v_cndmask_b32_e32 v93, v55, v85, vcc
	s_waitcnt vmcnt(0)
	v_pk_fma_f32 v[16:17], v[16:17], v[74:75], v[96:97]
	v_pk_fma_f32 v[14:15], v[14:15], v[76:77], v[94:95]
	v_cvt_pk_bf16_f32 v74, v14, v15
	v_cvt_pk_bf16_f32 v75, v16, v17
	global_store_dwordx2 v[82:83], v[74:75], off offset:2048
	global_load_dwordx4 v[74:77], v[98:99], off offset:1024
	s_nop 0
	global_load_dwordx4 v[78:81], v[100:101], off offset:1024
	v_cmp_lt_i32_e32 vcc, v87, v86
	s_waitcnt vmcnt(1)
	v_pk_add_f32 v[76:77], v[76:77], 1.0 op_sel_hi:[1,0]
	v_pk_add_f32 v[94:95], v[74:75], 1.0 op_sel_hi:[1,0]
	s_waitcnt vmcnt(0)
	v_pk_fma_f32 v[74:75], v[12:13], v[76:77], v[80:81]
	v_pk_fma_f32 v[76:77], v[10:11], v[94:95], v[78:79]
	v_cvt_pk_bf16_f32 v10, v76, v77
	v_cvt_pk_bf16_f32 v11, v74, v75
	global_store_dwordx2 v[82:83], v[10:11], off offset:2560
	global_load_dwordx4 v[10:13], v[98:99], off offset:2048
	s_nop 0
	global_load_dwordx4 v[94:97], v[100:101], off offset:2048
	s_waitcnt vmcnt(1)
	v_pk_add_f32 v[12:13], v[12:13], 1.0 op_sel_hi:[1,0]
	v_pk_add_f32 v[10:11], v[10:11], 1.0 op_sel_hi:[1,0]
	s_waitcnt vmcnt(0)
	v_pk_fma_f32 v[78:79], v[8:9], v[12:13], v[96:97]
	v_pk_fma_f32 v[80:81], v[6:7], v[10:11], v[94:95]
	v_cvt_pk_bf16_f32 v6, v80, v81
	v_cvt_pk_bf16_f32 v7, v78, v79
	global_store_dwordx2 v[82:83], v[6:7], off offset:3072
	global_load_dwordx4 v[10:13], v[98:99], off offset:3072
	s_nop 0
	global_load_dwordx4 v[6:9], v[100:101], off offset:3072
	v_cndmask_b32_e32 v94, v55, v87, vcc
	v_cmp_lt_i32_e32 vcc, v88, v86
	v_lshlrev_b32_e32 v95, 2, v93
	v_lshlrev_b32_e32 v94, 2, v94
	v_cndmask_b32_e32 v97, v55, v88, vcc
	v_lshlrev_b32_e32 v93, 2, v97
	v_cmp_lt_i32_e32 vcc, v89, v86
	s_waitcnt vmcnt(1)
	v_pk_add_f32 v[12:13], v[12:13], 1.0 op_sel_hi:[1,0]
	v_pk_add_f32 v[10:11], v[10:11], 1.0 op_sel_hi:[1,0]
	s_waitcnt vmcnt(0)
	v_pk_fma_f32 v[4:5], v[4:5], v[12:13], v[8:9]
	v_pk_fma_f32 v[2:3], v[2:3], v[10:11], v[6:7]
	v_cvt_pk_bf16_f32 v6, v2, v3
	v_cvt_pk_bf16_f32 v7, v4, v5
	global_store_dwordx2 v[82:83], v[6:7], off offset:3584
	s_load_dwordx2 s[50:51], s[6:7], 0x68
	v_lshl_add_u32 v97, v60, 4, 0
	ds_read_b128 v[6:9], v97
	ds_read_b128 v[10:13], v97 offset:1024
	ds_read_b128 v[140:143], v97 offset:2048
	ds_read_b128 v[144:147], v97 offset:3072
	ds_read_b128 v[148:151], v97 offset:4096
	ds_read_b128 v[152:155], v97 offset:5120
	ds_read_b128 v[156:159], v97 offset:6144
	ds_read_b128 v[160:163], v97 offset:7168
	s_waitcnt lgkmcnt(0)
	v_pk_fma_f32 v[82:83], v[64:65], v[6:7], 0 op_sel_hi:[1,1,0]
	v_pk_fma_f32 v[6:7], v[30:31], v[6:7], 0 op_sel_hi:[1,1,0]
	v_pk_fma_f32 v[82:83], v[62:63], v[8:9], v[82:83]
	v_pk_fma_f32 v[6:7], v[32:33], v[8:9], v[6:7]
	v_pk_fma_f32 v[8:9], v[68:69], v[10:11], v[82:83]
	v_pk_fma_f32 v[6:7], v[26:27], v[10:11], v[6:7]
	v_pk_fma_f32 v[8:9], v[66:67], v[12:13], v[8:9]
	v_pk_fma_f32 v[6:7], v[28:29], v[12:13], v[6:7]
	v_pk_fma_f32 v[8:9], v[72:73], v[140:141], v[8:9]
	v_pk_fma_f32 v[6:7], v[22:23], v[140:141], v[6:7]
	v_pk_fma_f32 v[8:9], v[70:71], v[142:143], v[8:9]
	v_pk_fma_f32 v[6:7], v[24:25], v[142:143], v[6:7]
	v_pk_fma_f32 v[8:9], v[50:51], v[144:145], v[8:9]
	v_pk_fma_f32 v[6:7], v[18:19], v[144:145], v[6:7]
	v_pk_fma_f32 v[8:9], v[52:53], v[146:147], v[8:9]
	v_pk_fma_f32 v[6:7], v[20:21], v[146:147], v[6:7]
	v_pk_fma_f32 v[8:9], v[46:47], v[148:149], v[8:9]
	v_pk_fma_f32 v[6:7], v[14:15], v[148:149], v[6:7]
	v_pk_fma_f32 v[8:9], v[48:49], v[150:151], v[8:9]
	v_pk_fma_f32 v[6:7], v[16:17], v[150:151], v[6:7]
	v_pk_fma_f32 v[8:9], v[42:43], v[152:153], v[8:9]
	v_pk_fma_f32 v[6:7], v[76:77], v[152:153], v[6:7]
	v_pk_fma_f32 v[8:9], v[44:45], v[154:155], v[8:9]
	v_pk_fma_f32 v[6:7], v[74:75], v[154:155], v[6:7]
	v_pk_fma_f32 v[8:9], v[38:39], v[156:157], v[8:9]
	v_pk_fma_f32 v[6:7], v[80:81], v[156:157], v[6:7]
	v_pk_fma_f32 v[8:9], v[40:41], v[158:159], v[8:9]
	v_pk_fma_f32 v[6:7], v[78:79], v[158:159], v[6:7]
	v_pk_fma_f32 v[8:9], v[34:35], v[160:161], v[8:9]
	v_pk_fma_f32 v[6:7], v[2:3], v[160:161], v[6:7]
	v_pk_fma_f32 v[8:9], v[36:37], v[162:163], v[8:9]
	v_pk_fma_f32 v[6:7], v[4:5], v[162:163], v[6:7]
	v_add_f32_e32 v197, v8, v9
	v_add_f32_e32 v6, v6, v7
	ds_read_b128 v[8:11], v97 offset:8192
	ds_read_b128 v[140:143], v97 offset:9216
	ds_read_b128 v[144:147], v97 offset:10240
	ds_read_b128 v[148:151], v97 offset:11264
	ds_read_b128 v[152:155], v97 offset:12288
	ds_read_b128 v[156:159], v97 offset:13312
	ds_read_b128 v[160:163], v97 offset:14336
	ds_read_b128 v[164:167], v97 offset:15360
	s_waitcnt lgkmcnt(7)
	v_pk_fma_f32 v[12:13], v[64:65], v[8:9], 0 op_sel_hi:[1,1,0]
	v_pk_fma_f32 v[8:9], v[30:31], v[8:9], 0 op_sel_hi:[1,1,0]
	v_pk_fma_f32 v[12:13], v[62:63], v[10:11], v[12:13]
	v_pk_fma_f32 v[8:9], v[32:33], v[10:11], v[8:9]
	s_waitcnt lgkmcnt(6)
	v_pk_fma_f32 v[10:11], v[68:69], v[140:141], v[12:13]
	v_pk_fma_f32 v[8:9], v[26:27], v[140:141], v[8:9]
	v_pk_fma_f32 v[10:11], v[66:67], v[142:143], v[10:11]
	v_pk_fma_f32 v[8:9], v[28:29], v[142:143], v[8:9]
	s_waitcnt lgkmcnt(5)
	v_pk_fma_f32 v[10:11], v[72:73], v[144:145], v[10:11]
	v_pk_fma_f32 v[8:9], v[22:23], v[144:145], v[8:9]
	v_pk_fma_f32 v[10:11], v[70:71], v[146:147], v[10:11]
	v_pk_fma_f32 v[8:9], v[24:25], v[146:147], v[8:9]
	s_waitcnt lgkmcnt(4)
	v_pk_fma_f32 v[10:11], v[50:51], v[148:149], v[10:11]
	v_pk_fma_f32 v[8:9], v[18:19], v[148:149], v[8:9]
	v_pk_fma_f32 v[10:11], v[52:53], v[150:151], v[10:11]
	v_pk_fma_f32 v[8:9], v[20:21], v[150:151], v[8:9]
	s_waitcnt lgkmcnt(3)
	v_pk_fma_f32 v[10:11], v[46:47], v[152:153], v[10:11]
	v_pk_fma_f32 v[8:9], v[14:15], v[152:153], v[8:9]
	v_pk_fma_f32 v[10:11], v[48:49], v[154:155], v[10:11]
	v_pk_fma_f32 v[8:9], v[16:17], v[154:155], v[8:9]
	s_waitcnt lgkmcnt(2)
	v_pk_fma_f32 v[10:11], v[42:43], v[156:157], v[10:11]
	v_pk_fma_f32 v[8:9], v[76:77], v[156:157], v[8:9]
	v_pk_fma_f32 v[10:11], v[44:45], v[158:159], v[10:11]
	v_pk_fma_f32 v[8:9], v[74:75], v[158:159], v[8:9]
	s_waitcnt lgkmcnt(1)
	v_pk_fma_f32 v[10:11], v[38:39], v[160:161], v[10:11]
	v_pk_fma_f32 v[8:9], v[80:81], v[160:161], v[8:9]
	v_pk_fma_f32 v[10:11], v[40:41], v[162:163], v[10:11]
	v_pk_fma_f32 v[8:9], v[78:79], v[162:163], v[8:9]
	s_waitcnt lgkmcnt(0)
	v_pk_fma_f32 v[10:11], v[34:35], v[164:165], v[10:11]
	v_pk_fma_f32 v[8:9], v[2:3], v[164:165], v[8:9]
	v_pk_fma_f32 v[10:11], v[36:37], v[166:167], v[10:11]
	v_pk_fma_f32 v[8:9], v[4:5], v[166:167], v[8:9]
	v_add_f32_e32 v198, v10, v11
	v_add_f32_e32 v7, v8, v9
	ds_read_b128 v[8:11], v97 offset:16384
	ds_read_b128 v[140:143], v97 offset:17408
	ds_read_b128 v[144:147], v97 offset:18432
	ds_read_b128 v[148:151], v97 offset:19456
	ds_read_b128 v[152:155], v97 offset:20480
	ds_read_b128 v[156:159], v97 offset:21504
	ds_read_b128 v[160:163], v97 offset:22528
	ds_read_b128 v[164:167], v97 offset:23552
	s_waitcnt lgkmcnt(7)
	v_pk_fma_f32 v[12:13], v[64:65], v[8:9], 0 op_sel_hi:[1,1,0]
	v_pk_fma_f32 v[8:9], v[30:31], v[8:9], 0 op_sel_hi:[1,1,0]
	v_pk_fma_f32 v[12:13], v[62:63], v[10:11], v[12:13]
	v_pk_fma_f32 v[8:9], v[32:33], v[10:11], v[8:9]
	s_waitcnt lgkmcnt(6)
	v_pk_fma_f32 v[10:11], v[68:69], v[140:141], v[12:13]
	v_pk_fma_f32 v[8:9], v[26:27], v[140:141], v[8:9]
	v_pk_fma_f32 v[10:11], v[66:67], v[142:143], v[10:11]
	v_pk_fma_f32 v[8:9], v[28:29], v[142:143], v[8:9]
	s_waitcnt lgkmcnt(5)
	v_pk_fma_f32 v[10:11], v[72:73], v[144:145], v[10:11]
	v_pk_fma_f32 v[8:9], v[22:23], v[144:145], v[8:9]
	v_pk_fma_f32 v[10:11], v[70:71], v[146:147], v[10:11]
	v_pk_fma_f32 v[8:9], v[24:25], v[146:147], v[8:9]
	s_waitcnt lgkmcnt(4)
	v_pk_fma_f32 v[10:11], v[50:51], v[148:149], v[10:11]
	v_pk_fma_f32 v[8:9], v[18:19], v[148:149], v[8:9]
	v_pk_fma_f32 v[10:11], v[52:53], v[150:151], v[10:11]
	v_pk_fma_f32 v[8:9], v[20:21], v[150:151], v[8:9]
	s_waitcnt lgkmcnt(3)
	v_pk_fma_f32 v[10:11], v[46:47], v[152:153], v[10:11]
	v_pk_fma_f32 v[8:9], v[14:15], v[152:153], v[8:9]
	v_pk_fma_f32 v[10:11], v[48:49], v[154:155], v[10:11]
	v_pk_fma_f32 v[8:9], v[16:17], v[154:155], v[8:9]
	s_waitcnt lgkmcnt(2)
	v_pk_fma_f32 v[10:11], v[42:43], v[156:157], v[10:11]
	v_pk_fma_f32 v[8:9], v[76:77], v[156:157], v[8:9]
	v_pk_fma_f32 v[10:11], v[44:45], v[158:159], v[10:11]
	v_pk_fma_f32 v[8:9], v[74:75], v[158:159], v[8:9]
	s_waitcnt lgkmcnt(1)
	v_pk_fma_f32 v[10:11], v[38:39], v[160:161], v[10:11]
	v_pk_fma_f32 v[8:9], v[80:81], v[160:161], v[8:9]
	v_pk_fma_f32 v[10:11], v[40:41], v[162:163], v[10:11]
	v_pk_fma_f32 v[8:9], v[78:79], v[162:163], v[8:9]
	s_waitcnt lgkmcnt(0)
	v_pk_fma_f32 v[10:11], v[34:35], v[164:165], v[10:11]
	v_pk_fma_f32 v[8:9], v[2:3], v[164:165], v[8:9]
	v_pk_fma_f32 v[10:11], v[36:37], v[166:167], v[10:11]
	v_pk_fma_f32 v[8:9], v[4:5], v[166:167], v[8:9]
	v_add_f32_e32 v199, v10, v11
	v_add_f32_e32 v8, v8, v9
	ds_read_b128 v[10:13], v97 offset:24576
	ds_read_b128 v[140:143], v97 offset:25600
	ds_read_b128 v[144:147], v97 offset:26624
	ds_read_b128 v[148:151], v97 offset:27648
	ds_read_b128 v[152:155], v97 offset:28672
	ds_read_b128 v[156:159], v97 offset:29696
	ds_read_b128 v[160:163], v97 offset:30720
	ds_read_b128 v[164:167], v97 offset:31744
	s_waitcnt lgkmcnt(7)
	v_pk_fma_f32 v[82:83], v[64:65], v[10:11], 0 op_sel_hi:[1,1,0]
	v_pk_fma_f32 v[10:11], v[30:31], v[10:11], 0 op_sel_hi:[1,1,0]
	v_pk_fma_f32 v[82:83], v[62:63], v[12:13], v[82:83]
	v_pk_fma_f32 v[10:11], v[32:33], v[12:13], v[10:11]
	s_waitcnt lgkmcnt(6)
	v_pk_fma_f32 v[12:13], v[68:69], v[140:141], v[82:83]
	v_pk_fma_f32 v[10:11], v[26:27], v[140:141], v[10:11]
	v_pk_fma_f32 v[12:13], v[66:67], v[142:143], v[12:13]
	v_pk_fma_f32 v[10:11], v[28:29], v[142:143], v[10:11]
	s_waitcnt lgkmcnt(5)
	v_pk_fma_f32 v[12:13], v[72:73], v[144:145], v[12:13]
	v_pk_fma_f32 v[10:11], v[22:23], v[144:145], v[10:11]
	v_pk_fma_f32 v[12:13], v[70:71], v[146:147], v[12:13]
	v_pk_fma_f32 v[10:11], v[24:25], v[146:147], v[10:11]
	s_waitcnt lgkmcnt(4)
	v_pk_fma_f32 v[12:13], v[50:51], v[148:149], v[12:13]
	v_pk_fma_f32 v[10:11], v[18:19], v[148:149], v[10:11]
	v_pk_fma_f32 v[12:13], v[52:53], v[150:151], v[12:13]
	v_pk_fma_f32 v[10:11], v[20:21], v[150:151], v[10:11]
	s_waitcnt lgkmcnt(3)
	v_pk_fma_f32 v[12:13], v[46:47], v[152:153], v[12:13]
	v_pk_fma_f32 v[10:11], v[14:15], v[152:153], v[10:11]
	v_pk_fma_f32 v[12:13], v[48:49], v[154:155], v[12:13]
	v_pk_fma_f32 v[10:11], v[16:17], v[154:155], v[10:11]
	s_waitcnt lgkmcnt(2)
	v_pk_fma_f32 v[12:13], v[42:43], v[156:157], v[12:13]
	v_pk_fma_f32 v[10:11], v[76:77], v[156:157], v[10:11]
	v_pk_fma_f32 v[12:13], v[44:45], v[158:159], v[12:13]
	v_pk_fma_f32 v[10:11], v[74:75], v[158:159], v[10:11]
	s_waitcnt lgkmcnt(1)
	v_pk_fma_f32 v[12:13], v[38:39], v[160:161], v[12:13]
	v_pk_fma_f32 v[10:11], v[80:81], v[160:161], v[10:11]
	v_pk_fma_f32 v[12:13], v[40:41], v[162:163], v[12:13]
	v_pk_fma_f32 v[10:11], v[78:79], v[162:163], v[10:11]
	s_waitcnt lgkmcnt(0)
	v_pk_fma_f32 v[12:13], v[34:35], v[164:165], v[12:13]
	v_pk_fma_f32 v[10:11], v[2:3], v[164:165], v[10:11]
	v_pk_fma_f32 v[12:13], v[36:37], v[166:167], v[12:13]
	v_pk_fma_f32 v[10:11], v[4:5], v[166:167], v[10:11]
	v_add_f32_e32 v200, v12, v13
	v_add_f32_e32 v9, v10, v11
	ds_read_b128 v[10:13], v97 offset:32768
	ds_read_b128 v[140:143], v97 offset:33792
	ds_read_b128 v[144:147], v97 offset:34816
	ds_read_b128 v[148:151], v97 offset:35840
	ds_read_b128 v[152:155], v97 offset:36864
	ds_read_b128 v[156:159], v97 offset:37888
	ds_read_b128 v[160:163], v97 offset:38912
	ds_read_b128 v[164:167], v97 offset:39936
	s_waitcnt lgkmcnt(7)
	v_pk_fma_f32 v[82:83], v[64:65], v[10:11], 0 op_sel_hi:[1,1,0]
	v_pk_fma_f32 v[10:11], v[30:31], v[10:11], 0 op_sel_hi:[1,1,0]
	v_pk_fma_f32 v[82:83], v[62:63], v[12:13], v[82:83]
	v_pk_fma_f32 v[10:11], v[32:33], v[12:13], v[10:11]
	s_waitcnt lgkmcnt(6)
	v_pk_fma_f32 v[12:13], v[68:69], v[140:141], v[82:83]
	v_pk_fma_f32 v[10:11], v[26:27], v[140:141], v[10:11]
	v_pk_fma_f32 v[12:13], v[66:67], v[142:143], v[12:13]
	v_pk_fma_f32 v[10:11], v[28:29], v[142:143], v[10:11]
	s_waitcnt lgkmcnt(5)
	v_pk_fma_f32 v[12:13], v[72:73], v[144:145], v[12:13]
	v_pk_fma_f32 v[10:11], v[22:23], v[144:145], v[10:11]
	v_pk_fma_f32 v[12:13], v[70:71], v[146:147], v[12:13]
	v_pk_fma_f32 v[10:11], v[24:25], v[146:147], v[10:11]
	s_waitcnt lgkmcnt(4)
	v_pk_fma_f32 v[12:13], v[50:51], v[148:149], v[12:13]
	v_pk_fma_f32 v[10:11], v[18:19], v[148:149], v[10:11]
	v_pk_fma_f32 v[12:13], v[52:53], v[150:151], v[12:13]
	v_pk_fma_f32 v[10:11], v[20:21], v[150:151], v[10:11]
	s_waitcnt lgkmcnt(3)
	v_pk_fma_f32 v[12:13], v[46:47], v[152:153], v[12:13]
	v_pk_fma_f32 v[10:11], v[14:15], v[152:153], v[10:11]
	v_pk_fma_f32 v[12:13], v[48:49], v[154:155], v[12:13]
	v_pk_fma_f32 v[10:11], v[16:17], v[154:155], v[10:11]
	s_waitcnt lgkmcnt(2)
	v_pk_fma_f32 v[12:13], v[42:43], v[156:157], v[12:13]
	v_pk_fma_f32 v[10:11], v[76:77], v[156:157], v[10:11]
	v_pk_fma_f32 v[12:13], v[44:45], v[158:159], v[12:13]
	v_pk_fma_f32 v[10:11], v[74:75], v[158:159], v[10:11]
	s_waitcnt lgkmcnt(1)
	v_pk_fma_f32 v[12:13], v[38:39], v[160:161], v[12:13]
	v_pk_fma_f32 v[10:11], v[80:81], v[160:161], v[10:11]
	v_pk_fma_f32 v[12:13], v[40:41], v[162:163], v[12:13]
	v_pk_fma_f32 v[10:11], v[78:79], v[162:163], v[10:11]
	s_waitcnt lgkmcnt(0)
	v_pk_fma_f32 v[12:13], v[34:35], v[164:165], v[12:13]
	v_pk_fma_f32 v[10:11], v[2:3], v[164:165], v[10:11]
	v_pk_fma_f32 v[12:13], v[36:37], v[166:167], v[12:13]
	v_pk_fma_f32 v[10:11], v[4:5], v[166:167], v[10:11]
	v_add_f32_e32 v201, v12, v13
	v_add_f32_e32 v10, v10, v11
	ds_read_b128 v[140:143], v97 offset:40960
	ds_read_b128 v[144:147], v97 offset:41984
	ds_read_b128 v[148:151], v97 offset:43008
	ds_read_b128 v[152:155], v97 offset:44032
	ds_read_b128 v[156:159], v97 offset:45056
	ds_read_b128 v[160:163], v97 offset:46080
	ds_read_b128 v[164:167], v97 offset:47104
	ds_read_b128 v[168:171], v97 offset:48128
	s_waitcnt lgkmcnt(7)
	v_pk_fma_f32 v[12:13], v[64:65], v[140:141], 0 op_sel_hi:[1,1,0]
	v_pk_fma_f32 v[82:83], v[30:31], v[140:141], 0 op_sel_hi:[1,1,0]
	v_pk_fma_f32 v[12:13], v[62:63], v[142:143], v[12:13]
	v_pk_fma_f32 v[82:83], v[32:33], v[142:143], v[82:83]
	s_waitcnt lgkmcnt(6)
	v_pk_fma_f32 v[12:13], v[68:69], v[144:145], v[12:13]
	v_pk_fma_f32 v[82:83], v[26:27], v[144:145], v[82:83]
	v_pk_fma_f32 v[12:13], v[66:67], v[146:147], v[12:13]
	v_pk_fma_f32 v[82:83], v[28:29], v[146:147], v[82:83]
	s_waitcnt lgkmcnt(5)
	v_pk_fma_f32 v[12:13], v[72:73], v[148:149], v[12:13]
	v_pk_fma_f32 v[82:83], v[22:23], v[148:149], v[82:83]
	v_pk_fma_f32 v[12:13], v[70:71], v[150:151], v[12:13]
	v_pk_fma_f32 v[82:83], v[24:25], v[150:151], v[82:83]
	s_waitcnt lgkmcnt(4)
	v_pk_fma_f32 v[12:13], v[50:51], v[152:153], v[12:13]
	v_pk_fma_f32 v[82:83], v[18:19], v[152:153], v[82:83]
	v_pk_fma_f32 v[12:13], v[52:53], v[154:155], v[12:13]
	v_pk_fma_f32 v[82:83], v[20:21], v[154:155], v[82:83]
	s_waitcnt lgkmcnt(3)
	v_pk_fma_f32 v[12:13], v[46:47], v[156:157], v[12:13]
	v_pk_fma_f32 v[82:83], v[14:15], v[156:157], v[82:83]
	v_pk_fma_f32 v[12:13], v[48:49], v[158:159], v[12:13]
	v_pk_fma_f32 v[82:83], v[16:17], v[158:159], v[82:83]
	s_waitcnt lgkmcnt(2)
	v_pk_fma_f32 v[12:13], v[42:43], v[160:161], v[12:13]
	v_pk_fma_f32 v[82:83], v[76:77], v[160:161], v[82:83]
	v_pk_fma_f32 v[12:13], v[44:45], v[162:163], v[12:13]
	v_pk_fma_f32 v[82:83], v[74:75], v[162:163], v[82:83]
	s_waitcnt lgkmcnt(1)
	v_pk_fma_f32 v[12:13], v[38:39], v[164:165], v[12:13]
	v_pk_fma_f32 v[82:83], v[80:81], v[164:165], v[82:83]
	v_pk_fma_f32 v[12:13], v[40:41], v[166:167], v[12:13]
	v_pk_fma_f32 v[82:83], v[78:79], v[166:167], v[82:83]
	s_waitcnt lgkmcnt(0)
	v_pk_fma_f32 v[12:13], v[34:35], v[168:169], v[12:13]
	v_pk_fma_f32 v[82:83], v[2:3], v[168:169], v[82:83]
	v_pk_fma_f32 v[12:13], v[36:37], v[170:171], v[12:13]
	v_pk_fma_f32 v[82:83], v[4:5], v[170:171], v[82:83]
	v_add_f32_e32 v202, v12, v13
	v_add_f32_e32 v11, v82, v83
	ds_read_b128 v[140:143], v97 offset:49152
	ds_read_b128 v[144:147], v97 offset:50176
	ds_read_b128 v[148:151], v97 offset:51200
	ds_read_b128 v[152:155], v97 offset:52224
	ds_read_b128 v[156:159], v97 offset:53248
	ds_read_b128 v[160:163], v97 offset:54272
	ds_read_b128 v[164:167], v97 offset:55296
	ds_read_b128 v[168:171], v97 offset:56320
	s_waitcnt lgkmcnt(7)
	v_pk_fma_f32 v[12:13], v[64:65], v[140:141], 0 op_sel_hi:[1,1,0]
	v_pk_fma_f32 v[82:83], v[30:31], v[140:141], 0 op_sel_hi:[1,1,0]
	v_pk_fma_f32 v[12:13], v[62:63], v[142:143], v[12:13]
	v_pk_fma_f32 v[82:83], v[32:33], v[142:143], v[82:83]
	s_waitcnt lgkmcnt(6)
	v_pk_fma_f32 v[12:13], v[68:69], v[144:145], v[12:13]
	v_pk_fma_f32 v[82:83], v[26:27], v[144:145], v[82:83]
	v_pk_fma_f32 v[12:13], v[66:67], v[146:147], v[12:13]
	v_pk_fma_f32 v[82:83], v[28:29], v[146:147], v[82:83]
	s_waitcnt lgkmcnt(5)
	v_pk_fma_f32 v[12:13], v[72:73], v[148:149], v[12:13]
	v_pk_fma_f32 v[82:83], v[22:23], v[148:149], v[82:83]
	v_pk_fma_f32 v[12:13], v[70:71], v[150:151], v[12:13]
	v_pk_fma_f32 v[82:83], v[24:25], v[150:151], v[82:83]
	s_waitcnt lgkmcnt(4)
	v_pk_fma_f32 v[12:13], v[50:51], v[152:153], v[12:13]
	v_pk_fma_f32 v[82:83], v[18:19], v[152:153], v[82:83]
	v_pk_fma_f32 v[12:13], v[52:53], v[154:155], v[12:13]
	v_pk_fma_f32 v[82:83], v[20:21], v[154:155], v[82:83]
	s_waitcnt lgkmcnt(3)
	v_pk_fma_f32 v[12:13], v[46:47], v[156:157], v[12:13]
	v_pk_fma_f32 v[82:83], v[14:15], v[156:157], v[82:83]
	v_pk_fma_f32 v[12:13], v[48:49], v[158:159], v[12:13]
	v_pk_fma_f32 v[82:83], v[16:17], v[158:159], v[82:83]
	s_waitcnt lgkmcnt(2)
	v_pk_fma_f32 v[12:13], v[42:43], v[160:161], v[12:13]
	v_pk_fma_f32 v[82:83], v[76:77], v[160:161], v[82:83]
	v_pk_fma_f32 v[12:13], v[44:45], v[162:163], v[12:13]
	v_pk_fma_f32 v[82:83], v[74:75], v[162:163], v[82:83]
	s_waitcnt lgkmcnt(1)
	v_pk_fma_f32 v[12:13], v[38:39], v[164:165], v[12:13]
	v_pk_fma_f32 v[82:83], v[80:81], v[164:165], v[82:83]
	v_pk_fma_f32 v[12:13], v[40:41], v[166:167], v[12:13]
	v_pk_fma_f32 v[82:83], v[78:79], v[166:167], v[82:83]
	s_waitcnt lgkmcnt(0)
	v_pk_fma_f32 v[12:13], v[34:35], v[168:169], v[12:13]
	v_pk_fma_f32 v[82:83], v[2:3], v[168:169], v[82:83]
	v_pk_fma_f32 v[12:13], v[36:37], v[170:171], v[12:13]
	v_pk_fma_f32 v[82:83], v[4:5], v[170:171], v[82:83]
	v_add_f32_e32 v203, v12, v13
	v_add_f32_e32 v12, v82, v83
	ds_read_b128 v[140:143], v97 offset:57344
	ds_read_b128 v[144:147], v97 offset:58368
	ds_read_b128 v[148:151], v97 offset:59392
	ds_read_b128 v[152:155], v97 offset:60416
	ds_read_b128 v[156:159], v97 offset:61440
	ds_read_b128 v[160:163], v97 offset:62464
	ds_read_b128 v[164:167], v97 offset:63488
	ds_read_b128 v[168:171], v97 offset:64512
	s_waitcnt lgkmcnt(7)
	v_pk_fma_f32 v[82:83], v[64:65], v[140:141], 0 op_sel_hi:[1,1,0]
	v_pk_fma_f32 v[140:141], v[30:31], v[140:141], 0 op_sel_hi:[1,1,0]
	v_pk_fma_f32 v[82:83], v[62:63], v[142:143], v[82:83]
	v_pk_fma_f32 v[140:141], v[32:33], v[142:143], v[140:141]
	s_waitcnt lgkmcnt(6)
	v_pk_fma_f32 v[82:83], v[68:69], v[144:145], v[82:83]
	v_pk_fma_f32 v[140:141], v[26:27], v[144:145], v[140:141]
	v_pk_fma_f32 v[82:83], v[66:67], v[146:147], v[82:83]
	v_pk_fma_f32 v[140:141], v[28:29], v[146:147], v[140:141]
	s_waitcnt lgkmcnt(5)
	v_pk_fma_f32 v[82:83], v[72:73], v[148:149], v[82:83]
	v_pk_fma_f32 v[140:141], v[22:23], v[148:149], v[140:141]
	v_pk_fma_f32 v[82:83], v[70:71], v[150:151], v[82:83]
	v_pk_fma_f32 v[140:141], v[24:25], v[150:151], v[140:141]
	s_waitcnt lgkmcnt(4)
	v_pk_fma_f32 v[82:83], v[50:51], v[152:153], v[82:83]
	v_pk_fma_f32 v[140:141], v[18:19], v[152:153], v[140:141]
	v_pk_fma_f32 v[82:83], v[52:53], v[154:155], v[82:83]
	v_pk_fma_f32 v[140:141], v[20:21], v[154:155], v[140:141]
	s_waitcnt lgkmcnt(3)
	v_pk_fma_f32 v[82:83], v[46:47], v[156:157], v[82:83]
	v_pk_fma_f32 v[140:141], v[14:15], v[156:157], v[140:141]
	v_pk_fma_f32 v[82:83], v[48:49], v[158:159], v[82:83]
	v_pk_fma_f32 v[140:141], v[16:17], v[158:159], v[140:141]
	s_waitcnt lgkmcnt(2)
	v_pk_fma_f32 v[82:83], v[42:43], v[160:161], v[82:83]
	v_pk_fma_f32 v[140:141], v[76:77], v[160:161], v[140:141]
	v_pk_fma_f32 v[82:83], v[44:45], v[162:163], v[82:83]
	v_pk_fma_f32 v[140:141], v[74:75], v[162:163], v[140:141]
	s_waitcnt lgkmcnt(1)
	v_pk_fma_f32 v[82:83], v[38:39], v[164:165], v[82:83]
	v_pk_fma_f32 v[140:141], v[80:81], v[164:165], v[140:141]
	v_pk_fma_f32 v[82:83], v[40:41], v[166:167], v[82:83]
	v_pk_fma_f32 v[140:141], v[78:79], v[166:167], v[140:141]
	s_waitcnt lgkmcnt(0)
	v_pk_fma_f32 v[82:83], v[34:35], v[168:169], v[82:83]
	v_pk_fma_f32 v[140:141], v[2:3], v[168:169], v[140:141]
	v_pk_fma_f32 v[82:83], v[36:37], v[170:171], v[82:83]
	v_pk_fma_f32 v[140:141], v[4:5], v[170:171], v[140:141]
	v_add_f32_e32 v204, v82, v83
	v_add_f32_e32 v13, v140, v141
	v_add_u32_e32 v173, 0x10000, v97
	v_add_u32_e32 v174, 0x10400, v97
	v_add_u32_e32 v175, 0x10800, v97
	v_add_u32_e32 v176, 0x10c00, v97
	v_add_u32_e32 v177, 0x11000, v97
	v_add_u32_e32 v178, 0x11400, v97
	v_add_u32_e32 v179, 0x11800, v97
	v_add_u32_e32 v180, 0x11c00, v97
	ds_read_b128 v[140:143], v173
	ds_read_b128 v[144:147], v174
	ds_read_b128 v[148:151], v175
	ds_read_b128 v[152:155], v176
	ds_read_b128 v[156:159], v177
	ds_read_b128 v[160:163], v178
	ds_read_b128 v[164:167], v179
	ds_read_b128 v[168:171], v180
	s_waitcnt lgkmcnt(7)
	v_pk_fma_f32 v[82:83], v[64:65], v[140:141], 0 op_sel_hi:[1,1,0]
	v_pk_fma_f32 v[140:141], v[30:31], v[140:141], 0 op_sel_hi:[1,1,0]
	v_pk_fma_f32 v[82:83], v[62:63], v[142:143], v[82:83]
	v_pk_fma_f32 v[140:141], v[32:33], v[142:143], v[140:141]
	s_waitcnt lgkmcnt(6)
	v_pk_fma_f32 v[82:83], v[68:69], v[144:145], v[82:83]
	v_pk_fma_f32 v[140:141], v[26:27], v[144:145], v[140:141]
	v_pk_fma_f32 v[82:83], v[66:67], v[146:147], v[82:83]
	v_pk_fma_f32 v[140:141], v[28:29], v[146:147], v[140:141]
	s_waitcnt lgkmcnt(5)
	v_pk_fma_f32 v[82:83], v[72:73], v[148:149], v[82:83]
	v_pk_fma_f32 v[140:141], v[22:23], v[148:149], v[140:141]
	v_pk_fma_f32 v[82:83], v[70:71], v[150:151], v[82:83]
	v_pk_fma_f32 v[140:141], v[24:25], v[150:151], v[140:141]
	s_waitcnt lgkmcnt(4)
	v_pk_fma_f32 v[82:83], v[50:51], v[152:153], v[82:83]
	v_pk_fma_f32 v[140:141], v[18:19], v[152:153], v[140:141]
	v_pk_fma_f32 v[82:83], v[52:53], v[154:155], v[82:83]
	v_pk_fma_f32 v[140:141], v[20:21], v[154:155], v[140:141]
	s_waitcnt lgkmcnt(3)
	v_pk_fma_f32 v[82:83], v[46:47], v[156:157], v[82:83]
	v_pk_fma_f32 v[140:141], v[14:15], v[156:157], v[140:141]
	v_pk_fma_f32 v[82:83], v[48:49], v[158:159], v[82:83]
	v_pk_fma_f32 v[140:141], v[16:17], v[158:159], v[140:141]
	s_waitcnt lgkmcnt(2)
	v_pk_fma_f32 v[82:83], v[42:43], v[160:161], v[82:83]
	v_pk_fma_f32 v[140:141], v[76:77], v[160:161], v[140:141]
	v_pk_fma_f32 v[82:83], v[44:45], v[162:163], v[82:83]
	v_pk_fma_f32 v[140:141], v[74:75], v[162:163], v[140:141]
	s_waitcnt lgkmcnt(1)
	v_pk_fma_f32 v[82:83], v[38:39], v[164:165], v[82:83]
	v_pk_fma_f32 v[140:141], v[80:81], v[164:165], v[140:141]
	v_pk_fma_f32 v[82:83], v[40:41], v[166:167], v[82:83]
	v_pk_fma_f32 v[140:141], v[78:79], v[166:167], v[140:141]
	s_waitcnt lgkmcnt(0)
	v_pk_fma_f32 v[82:83], v[34:35], v[168:169], v[82:83]
	v_pk_fma_f32 v[140:141], v[2:3], v[168:169], v[140:141]
	v_pk_fma_f32 v[82:83], v[36:37], v[170:171], v[82:83]
	v_pk_fma_f32 v[140:141], v[4:5], v[170:171], v[140:141]
	v_add_f32_e32 v83, v82, v83
	v_add_f32_e32 v82, v140, v141
	v_add_u32_e32 v181, 0x12000, v97
	v_and_b32_e32 v172, 32, v60
	v_add_u32_e32 v182, 0x12400, v97
	v_add_u32_e32 v183, 0x12800, v97
	v_add_u32_e32 v184, 0x12c00, v97
	v_add_u32_e32 v185, 0x13000, v97
	v_add_u32_e32 v186, 0x13400, v97
	v_add_u32_e32 v187, 0x13800, v97
	v_add_u32_e32 v188, 0x13c00, v97
	ds_read_b128 v[140:143], v181
	ds_read_b128 v[144:147], v182
	ds_read_b128 v[148:151], v183
	ds_read_b128 v[152:155], v184
	ds_read_b128 v[156:159], v185
	ds_read_b128 v[160:163], v186
	ds_read_b128 v[164:167], v187
	ds_read_b128 v[168:171], v188
	v_cndmask_b32_e32 v96, v55, v89, vcc
	v_cmp_eq_u32_e32 vcc, 0, v172
	s_waitcnt lgkmcnt(7)
	v_pk_fma_f32 v[172:173], v[64:65], v[140:141], 0 op_sel_hi:[1,1,0]
	v_pk_fma_f32 v[140:141], v[30:31], v[140:141], 0 op_sel_hi:[1,1,0]
	v_pk_fma_f32 v[172:173], v[62:63], v[142:143], v[172:173]
	v_pk_fma_f32 v[140:141], v[32:33], v[142:143], v[140:141]
	s_waitcnt lgkmcnt(6)
	v_pk_fma_f32 v[142:143], v[68:69], v[144:145], v[172:173]
	v_pk_fma_f32 v[140:141], v[26:27], v[144:145], v[140:141]
	v_pk_fma_f32 v[142:143], v[66:67], v[146:147], v[142:143]
	v_pk_fma_f32 v[140:141], v[28:29], v[146:147], v[140:141]
	s_waitcnt lgkmcnt(5)
	v_pk_fma_f32 v[142:143], v[72:73], v[148:149], v[142:143]
	v_pk_fma_f32 v[140:141], v[22:23], v[148:149], v[140:141]
	v_pk_fma_f32 v[142:143], v[70:71], v[150:151], v[142:143]
	v_pk_fma_f32 v[140:141], v[24:25], v[150:151], v[140:141]
	s_waitcnt lgkmcnt(4)
	v_pk_fma_f32 v[142:143], v[50:51], v[152:153], v[142:143]
	v_pk_fma_f32 v[140:141], v[18:19], v[152:153], v[140:141]
	v_pk_fma_f32 v[142:143], v[52:53], v[154:155], v[142:143]
	v_pk_fma_f32 v[140:141], v[20:21], v[154:155], v[140:141]
	s_waitcnt lgkmcnt(3)
	v_pk_fma_f32 v[142:143], v[46:47], v[156:157], v[142:143]
	v_pk_fma_f32 v[140:141], v[14:15], v[156:157], v[140:141]
	v_pk_fma_f32 v[142:143], v[48:49], v[158:159], v[142:143]
	v_pk_fma_f32 v[140:141], v[16:17], v[158:159], v[140:141]
	v_add_u32_e32 v189, 0x14000, v97
	v_add_u32_e32 v190, 0x14400, v97
	v_add_u32_e32 v191, 0x14800, v97
	v_add_u32_e32 v192, 0x14c00, v97
	v_add_u32_e32 v193, 0x15000, v97
	v_add_u32_e32 v194, 0x15400, v97
	v_add_u32_e32 v195, 0x15800, v97
	v_add_u32_e32 v196, 0x15c00, v97
	v_add_u32_e32 v98, 0x16000, v97
	v_add_u32_e32 v133, 0x16400, v97
	v_add_u32_e32 v134, 0x16800, v97
	v_add_u32_e32 v135, 0x16c00, v97
	v_add_u32_e32 v136, 0x17000, v97
	v_add_u32_e32 v137, 0x17400, v97
	v_add_u32_e32 v138, 0x17800, v97
	v_add_u32_e32 v139, 0x17c00, v97
	v_add_u32_e32 v99, 0x18000, v97
	v_add_u32_e32 v126, 0x18400, v97
	v_add_u32_e32 v127, 0x18800, v97
	v_add_u32_e32 v128, 0x18c00, v97
	v_add_u32_e32 v129, 0x19000, v97
	v_add_u32_e32 v130, 0x19400, v97
	v_add_u32_e32 v131, 0x19800, v97
	v_add_u32_e32 v132, 0x19c00, v97
	v_add_u32_e32 v118, 0x1a000, v97
	v_add_u32_e32 v119, 0x1a400, v97
	v_add_u32_e32 v120, 0x1a800, v97
	v_add_u32_e32 v121, 0x1ac00, v97
	v_add_u32_e32 v122, 0x1b000, v97
	v_add_u32_e32 v123, 0x1b400, v97
	v_add_u32_e32 v124, 0x1b800, v97
	v_add_u32_e32 v125, 0x1bc00, v97
	v_add_u32_e32 v101, 0x1c000, v97
	v_add_u32_e32 v111, 0x1c400, v97
	v_add_u32_e32 v112, 0x1c800, v97
	v_add_u32_e32 v113, 0x1cc00, v97
	v_add_u32_e32 v114, 0x1d000, v97
	v_add_u32_e32 v115, 0x1d400, v97
	v_add_u32_e32 v116, 0x1d800, v97
	v_add_u32_e32 v117, 0x1dc00, v97
	v_add_u32_e32 v103, 0x1e000, v97
	v_add_u32_e32 v104, 0x1e400, v97
	v_add_u32_e32 v105, 0x1e800, v97
	v_add_u32_e32 v106, 0x1ec00, v97
	v_add_u32_e32 v107, 0x1f000, v97
	v_add_u32_e32 v108, 0x1f400, v97
	v_add_u32_e32 v109, 0x1f800, v97
	v_add_u32_e32 v110, 0x1fc00, v97
	v_cndmask_b32_e32 v97, v83, v197, vcc
	v_cndmask_b32_e32 v83, v197, v83, vcc
	s_waitcnt lgkmcnt(2)
	v_pk_fma_f32 v[142:143], v[42:43], v[160:161], v[142:143]
	v_pk_fma_f32 v[140:141], v[76:77], v[160:161], v[140:141]
	ds_bpermute_b32 v83, v95, v83
	v_pk_fma_f32 v[142:143], v[44:45], v[162:163], v[142:143]
	v_pk_fma_f32 v[140:141], v[74:75], v[162:163], v[140:141]
	s_waitcnt lgkmcnt(2)
	v_pk_fma_f32 v[142:143], v[38:39], v[164:165], v[142:143]
	v_pk_fma_f32 v[140:141], v[80:81], v[164:165], v[140:141]
	v_pk_fma_f32 v[142:143], v[40:41], v[166:167], v[142:143]
	v_pk_fma_f32 v[140:141], v[78:79], v[166:167], v[140:141]
	s_waitcnt lgkmcnt(1)
	v_pk_fma_f32 v[142:143], v[34:35], v[168:169], v[142:143]
	v_pk_fma_f32 v[140:141], v[2:3], v[168:169], v[140:141]
	v_pk_fma_f32 v[142:143], v[36:37], v[170:171], v[142:143]
	v_pk_fma_f32 v[140:141], v[4:5], v[170:171], v[140:141]
	s_waitcnt lgkmcnt(0)
	v_add_f32_e32 v174, v97, v83
	v_add_f32_e32 v97, v142, v143
	v_add_f32_e32 v83, v140, v141
	ds_read_b128 v[140:143], v189
	ds_read_b128 v[144:147], v190
	ds_read_b128 v[148:151], v191
	ds_read_b128 v[152:155], v192
	ds_read_b128 v[156:159], v193
	ds_read_b128 v[160:163], v194
	ds_read_b128 v[164:167], v195
	ds_read_b128 v[168:171], v196
	s_waitcnt lgkmcnt(7)
	v_pk_fma_f32 v[172:173], v[64:65], v[140:141], 0 op_sel_hi:[1,1,0]
	v_pk_fma_f32 v[140:141], v[30:31], v[140:141], 0 op_sel_hi:[1,1,0]
	v_pk_fma_f32 v[172:173], v[62:63], v[142:143], v[172:173]
	v_pk_fma_f32 v[140:141], v[32:33], v[142:143], v[140:141]
	s_waitcnt lgkmcnt(6)
	v_pk_fma_f32 v[142:143], v[68:69], v[144:145], v[172:173]
	v_pk_fma_f32 v[140:141], v[26:27], v[144:145], v[140:141]
	v_pk_fma_f32 v[142:143], v[66:67], v[146:147], v[142:143]
	v_pk_fma_f32 v[140:141], v[28:29], v[146:147], v[140:141]
	s_waitcnt lgkmcnt(5)
	v_pk_fma_f32 v[142:143], v[72:73], v[148:149], v[142:143]
	v_pk_fma_f32 v[140:141], v[22:23], v[148:149], v[140:141]
	v_pk_fma_f32 v[142:143], v[70:71], v[150:151], v[142:143]
	v_pk_fma_f32 v[140:141], v[24:25], v[150:151], v[140:141]
	s_waitcnt lgkmcnt(4)
	v_pk_fma_f32 v[142:143], v[50:51], v[152:153], v[142:143]
	v_pk_fma_f32 v[140:141], v[18:19], v[152:153], v[140:141]
	v_pk_fma_f32 v[142:143], v[52:53], v[154:155], v[142:143]
	v_pk_fma_f32 v[140:141], v[20:21], v[154:155], v[140:141]
	s_waitcnt lgkmcnt(3)
	v_pk_fma_f32 v[142:143], v[46:47], v[156:157], v[142:143]
	v_pk_fma_f32 v[140:141], v[14:15], v[156:157], v[140:141]
	v_pk_fma_f32 v[142:143], v[48:49], v[158:159], v[142:143]
	v_pk_fma_f32 v[140:141], v[16:17], v[158:159], v[140:141]
	v_cndmask_b32_e32 v175, v97, v198, vcc
	v_cndmask_b32_e32 v97, v198, v97, vcc
	s_waitcnt lgkmcnt(2)
	v_pk_fma_f32 v[142:143], v[42:43], v[160:161], v[142:143]
	v_pk_fma_f32 v[140:141], v[76:77], v[160:161], v[140:141]
	ds_bpermute_b32 v97, v95, v97
	v_pk_fma_f32 v[142:143], v[44:45], v[162:163], v[142:143]
	v_pk_fma_f32 v[140:141], v[74:75], v[162:163], v[140:141]
	s_waitcnt lgkmcnt(2)
	v_pk_fma_f32 v[142:143], v[38:39], v[164:165], v[142:143]
	v_pk_fma_f32 v[140:141], v[80:81], v[164:165], v[140:141]
	v_pk_fma_f32 v[142:143], v[40:41], v[166:167], v[142:143]
	v_pk_fma_f32 v[140:141], v[78:79], v[166:167], v[140:141]
	s_waitcnt lgkmcnt(1)
	v_pk_fma_f32 v[142:143], v[34:35], v[168:169], v[142:143]
	v_pk_fma_f32 v[140:141], v[2:3], v[168:169], v[140:141]
	v_pk_fma_f32 v[142:143], v[36:37], v[170:171], v[142:143]
	v_pk_fma_f32 v[140:141], v[4:5], v[170:171], v[140:141]
	s_waitcnt lgkmcnt(0)
	v_add_f32_e32 v172, v175, v97
	v_add_f32_e32 v168, v142, v143
	v_add_f32_e32 v97, v140, v141
	ds_read_b128 v[140:143], v98
	ds_read_b128 v[144:147], v133
	ds_read_b128 v[148:151], v134
	ds_read_b128 v[152:155], v135
	ds_read_b128 v[156:159], v136
	ds_read_b128 v[134:137], v137
	ds_read_b128 v[160:163], v138
	ds_read_b128 v[164:167], v139
	s_waitcnt lgkmcnt(7)
	v_pk_fma_f32 v[138:139], v[64:65], v[140:141], 0 op_sel_hi:[1,1,0]
	v_pk_fma_f32 v[140:141], v[30:31], v[140:141], 0 op_sel_hi:[1,1,0]
	v_pk_fma_f32 v[138:139], v[62:63], v[142:143], v[138:139]
	v_pk_fma_f32 v[140:141], v[32:33], v[142:143], v[140:141]
	s_waitcnt lgkmcnt(6)
	v_pk_fma_f32 v[138:139], v[68:69], v[144:145], v[138:139]
	v_pk_fma_f32 v[140:141], v[26:27], v[144:145], v[140:141]
	v_pk_fma_f32 v[138:139], v[66:67], v[146:147], v[138:139]
	v_pk_fma_f32 v[140:141], v[28:29], v[146:147], v[140:141]
	s_waitcnt lgkmcnt(5)
	v_pk_fma_f32 v[138:139], v[72:73], v[148:149], v[138:139]
	v_pk_fma_f32 v[140:141], v[22:23], v[148:149], v[140:141]
	v_pk_fma_f32 v[138:139], v[70:71], v[150:151], v[138:139]
	v_pk_fma_f32 v[140:141], v[24:25], v[150:151], v[140:141]
	s_waitcnt lgkmcnt(4)
	v_pk_fma_f32 v[138:139], v[50:51], v[152:153], v[138:139]
	v_pk_fma_f32 v[140:141], v[18:19], v[152:153], v[140:141]
	v_pk_fma_f32 v[138:139], v[52:53], v[154:155], v[138:139]
	v_pk_fma_f32 v[140:141], v[20:21], v[154:155], v[140:141]
	s_waitcnt lgkmcnt(3)
	v_pk_fma_f32 v[138:139], v[46:47], v[156:157], v[138:139]
	v_pk_fma_f32 v[140:141], v[14:15], v[156:157], v[140:141]
	v_pk_fma_f32 v[138:139], v[48:49], v[158:159], v[138:139]
	v_pk_fma_f32 v[140:141], v[16:17], v[158:159], v[140:141]
	v_cndmask_b32_e32 v133, v199, v168, vcc
	s_waitcnt lgkmcnt(2)
	v_pk_fma_f32 v[138:139], v[42:43], v[134:135], v[138:139]
	v_pk_fma_f32 v[134:135], v[76:77], v[134:135], v[140:141]
	ds_bpermute_b32 v133, v95, v133
	v_pk_fma_f32 v[138:139], v[44:45], v[136:137], v[138:139]
	v_pk_fma_f32 v[134:135], v[74:75], v[136:137], v[134:135]
	s_waitcnt lgkmcnt(2)
	v_pk_fma_f32 v[136:137], v[38:39], v[160:161], v[138:139]
	v_pk_fma_f32 v[134:135], v[80:81], v[160:161], v[134:135]
	v_pk_fma_f32 v[136:137], v[40:41], v[162:163], v[136:137]
	v_pk_fma_f32 v[134:135], v[78:79], v[162:163], v[134:135]
	s_waitcnt lgkmcnt(1)
	v_pk_fma_f32 v[136:137], v[34:35], v[164:165], v[136:137]
	v_pk_fma_f32 v[134:135], v[2:3], v[164:165], v[134:135]
	v_cndmask_b32_e32 v98, v168, v199, vcc
	v_pk_fma_f32 v[136:137], v[36:37], v[166:167], v[136:137]
	v_pk_fma_f32 v[134:135], v[4:5], v[166:167], v[134:135]
	s_waitcnt lgkmcnt(0)
	v_add_f32_e32 v168, v98, v133
	v_add_f32_e32 v158, v136, v137
	v_add_f32_e32 v98, v134, v135
	ds_read_b128 v[134:137], v99
	ds_read_b128 v[138:141], v126
	ds_read_b128 v[142:145], v127
	ds_read_b128 v[146:149], v128
	ds_read_b128 v[126:129], v129
	ds_read_b128 v[150:153], v130
	ds_read_b128 v[154:157], v131
	ds_read_b128 v[130:133], v132
	v_cndmask_b32_e32 v99, v158, v200, vcc
	v_cndmask_b32_e32 v158, v200, v158, vcc
	ds_bpermute_b32 v160, v95, v158
	s_waitcnt lgkmcnt(8)
	v_pk_fma_f32 v[158:159], v[64:65], v[134:135], 0 op_sel_hi:[1,1,0]
	v_pk_fma_f32 v[134:135], v[30:31], v[134:135], 0 op_sel_hi:[1,1,0]
	v_pk_fma_f32 v[158:159], v[62:63], v[136:137], v[158:159]
	v_pk_fma_f32 v[134:135], v[32:33], v[136:137], v[134:135]
	s_waitcnt lgkmcnt(7)
	v_pk_fma_f32 v[136:137], v[68:69], v[138:139], v[158:159]
	v_pk_fma_f32 v[134:135], v[26:27], v[138:139], v[134:135]
	v_pk_fma_f32 v[136:137], v[66:67], v[140:141], v[136:137]
	v_pk_fma_f32 v[134:135], v[28:29], v[140:141], v[134:135]
	s_waitcnt lgkmcnt(6)
	v_pk_fma_f32 v[136:137], v[72:73], v[142:143], v[136:137]
	v_pk_fma_f32 v[134:135], v[22:23], v[142:143], v[134:135]
	v_pk_fma_f32 v[136:137], v[70:71], v[144:145], v[136:137]
	v_pk_fma_f32 v[134:135], v[24:25], v[144:145], v[134:135]
	s_waitcnt lgkmcnt(5)
	v_pk_fma_f32 v[136:137], v[50:51], v[146:147], v[136:137]
	v_pk_fma_f32 v[134:135], v[18:19], v[146:147], v[134:135]
	v_pk_fma_f32 v[136:137], v[52:53], v[148:149], v[136:137]
	v_pk_fma_f32 v[134:135], v[20:21], v[148:149], v[134:135]
	s_waitcnt lgkmcnt(4)
	v_pk_fma_f32 v[136:137], v[46:47], v[126:127], v[136:137]
	v_pk_fma_f32 v[126:127], v[14:15], v[126:127], v[134:135]
	v_pk_fma_f32 v[134:135], v[48:49], v[128:129], v[136:137]
	v_pk_fma_f32 v[126:127], v[16:17], v[128:129], v[126:127]
	s_waitcnt lgkmcnt(3)
	v_pk_fma_f32 v[128:129], v[42:43], v[150:151], v[134:135]
	v_pk_fma_f32 v[126:127], v[76:77], v[150:151], v[126:127]
	v_pk_fma_f32 v[128:129], v[44:45], v[152:153], v[128:129]
	v_pk_fma_f32 v[126:127], v[74:75], v[152:153], v[126:127]
	s_waitcnt lgkmcnt(2)
	v_pk_fma_f32 v[128:129], v[38:39], v[154:155], v[128:129]
	v_pk_fma_f32 v[126:127], v[80:81], v[154:155], v[126:127]
	v_pk_fma_f32 v[128:129], v[40:41], v[156:157], v[128:129]
	v_pk_fma_f32 v[126:127], v[78:79], v[156:157], v[126:127]
	s_waitcnt lgkmcnt(1)
	v_pk_fma_f32 v[128:129], v[34:35], v[130:131], v[128:129]
	v_pk_fma_f32 v[126:127], v[2:3], v[130:131], v[126:127]
	v_pk_fma_f32 v[128:129], v[36:37], v[132:133], v[128:129]
	v_pk_fma_f32 v[126:127], v[4:5], v[132:133], v[126:127]
	s_waitcnt lgkmcnt(0)
	v_add_f32_e32 v158, v99, v160
	v_add_f32_e32 v150, v128, v129
	v_add_f32_e32 v99, v126, v127
	ds_read_b128 v[126:129], v118
	ds_read_b128 v[130:133], v119
	ds_read_b128 v[134:137], v120
	ds_read_b128 v[118:121], v121
	ds_read_b128 v[138:141], v122
	ds_read_b128 v[142:145], v123
	ds_read_b128 v[146:149], v124
	ds_read_b128 v[122:125], v125
	v_cndmask_b32_e32 v152, v150, v201, vcc
	v_cndmask_b32_e32 v150, v201, v150, vcc
	ds_bpermute_b32 v153, v95, v150
	s_waitcnt lgkmcnt(8)
	v_pk_fma_f32 v[150:151], v[64:65], v[126:127], 0 op_sel_hi:[1,1,0]
	v_pk_fma_f32 v[126:127], v[30:31], v[126:127], 0 op_sel_hi:[1,1,0]
	v_pk_fma_f32 v[150:151], v[62:63], v[128:129], v[150:151]
	v_pk_fma_f32 v[126:127], v[32:33], v[128:129], v[126:127]
	s_waitcnt lgkmcnt(7)
	v_pk_fma_f32 v[128:129], v[68:69], v[130:131], v[150:151]
	v_pk_fma_f32 v[126:127], v[26:27], v[130:131], v[126:127]
	v_pk_fma_f32 v[128:129], v[66:67], v[132:133], v[128:129]
	v_pk_fma_f32 v[126:127], v[28:29], v[132:133], v[126:127]
	s_waitcnt lgkmcnt(6)
	v_pk_fma_f32 v[128:129], v[72:73], v[134:135], v[128:129]
	v_pk_fma_f32 v[126:127], v[22:23], v[134:135], v[126:127]
	v_pk_fma_f32 v[128:129], v[70:71], v[136:137], v[128:129]
	v_pk_fma_f32 v[126:127], v[24:25], v[136:137], v[126:127]
	s_waitcnt lgkmcnt(5)
	v_pk_fma_f32 v[128:129], v[50:51], v[118:119], v[128:129]
	v_pk_fma_f32 v[118:119], v[18:19], v[118:119], v[126:127]
	v_pk_fma_f32 v[126:127], v[52:53], v[120:121], v[128:129]
	v_pk_fma_f32 v[118:119], v[20:21], v[120:121], v[118:119]
	v_and_b32_e32 v100, 16, v60
	s_waitcnt lgkmcnt(4)
	v_pk_fma_f32 v[120:121], v[46:47], v[138:139], v[126:127]
	v_pk_fma_f32 v[118:119], v[14:15], v[138:139], v[118:119]
	s_waitcnt lgkmcnt(0)
	v_add_f32_e32 v130, v152, v153
	v_cmp_eq_u32_e64 s[8:9], 0, v100
	v_pk_fma_f32 v[120:121], v[48:49], v[140:141], v[120:121]
	v_pk_fma_f32 v[118:119], v[16:17], v[140:141], v[118:119]
	v_cndmask_b32_e64 v100, v130, v174, s[8:9]
	v_cndmask_b32_e64 v130, v174, v130, s[8:9]
	v_pk_fma_f32 v[120:121], v[42:43], v[142:143], v[120:121]
	v_pk_fma_f32 v[118:119], v[76:77], v[142:143], v[118:119]
	ds_bpermute_b32 v130, v94, v130
	v_pk_fma_f32 v[120:121], v[44:45], v[144:145], v[120:121]
	v_pk_fma_f32 v[118:119], v[74:75], v[144:145], v[118:119]
	v_pk_fma_f32 v[120:121], v[38:39], v[146:147], v[120:121]
	v_pk_fma_f32 v[118:119], v[80:81], v[146:147], v[118:119]
	v_pk_fma_f32 v[120:121], v[40:41], v[148:149], v[120:121]
	v_pk_fma_f32 v[118:119], v[78:79], v[148:149], v[118:119]
	v_pk_fma_f32 v[120:121], v[34:35], v[122:123], v[120:121]
	v_pk_fma_f32 v[118:119], v[2:3], v[122:123], v[118:119]
	v_pk_fma_f32 v[120:121], v[36:37], v[124:125], v[120:121]
	v_pk_fma_f32 v[118:119], v[4:5], v[124:125], v[118:119]
	s_waitcnt lgkmcnt(0)
	v_add_f32_e32 v150, v100, v130
	v_add_f32_e32 v146, v120, v121
	v_add_f32_e32 v100, v118, v119
	ds_read_b128 v[118:121], v101
	ds_read_b128 v[122:125], v111
	ds_read_b128 v[126:129], v112
	ds_read_b128 v[130:133], v113
	ds_read_b128 v[134:137], v114
	ds_read_b128 v[112:115], v115
	ds_read_b128 v[138:141], v116
	ds_read_b128 v[142:145], v117
	s_waitcnt lgkmcnt(7)
	v_pk_fma_f32 v[116:117], v[64:65], v[118:119], 0 op_sel_hi:[1,1,0]
	v_pk_fma_f32 v[118:119], v[30:31], v[118:119], 0 op_sel_hi:[1,1,0]
	v_pk_fma_f32 v[116:117], v[62:63], v[120:121], v[116:117]
	v_pk_fma_f32 v[118:119], v[32:33], v[120:121], v[118:119]
	s_waitcnt lgkmcnt(6)
	v_pk_fma_f32 v[116:117], v[68:69], v[122:123], v[116:117]
	v_pk_fma_f32 v[118:119], v[26:27], v[122:123], v[118:119]
	v_pk_fma_f32 v[116:117], v[66:67], v[124:125], v[116:117]
	v_pk_fma_f32 v[118:119], v[28:29], v[124:125], v[118:119]
	s_waitcnt lgkmcnt(5)
	v_pk_fma_f32 v[116:117], v[72:73], v[126:127], v[116:117]
	v_pk_fma_f32 v[118:119], v[22:23], v[126:127], v[118:119]
	v_pk_fma_f32 v[116:117], v[70:71], v[128:129], v[116:117]
	v_pk_fma_f32 v[118:119], v[24:25], v[128:129], v[118:119]
	s_waitcnt lgkmcnt(4)
	v_pk_fma_f32 v[116:117], v[50:51], v[130:131], v[116:117]
	v_pk_fma_f32 v[118:119], v[18:19], v[130:131], v[118:119]
	v_pk_fma_f32 v[116:117], v[52:53], v[132:133], v[116:117]
	v_pk_fma_f32 v[118:119], v[20:21], v[132:133], v[118:119]
	v_cndmask_b32_e32 v111, v202, v146, vcc
	s_waitcnt lgkmcnt(3)
	v_pk_fma_f32 v[116:117], v[46:47], v[134:135], v[116:117]
	v_pk_fma_f32 v[118:119], v[14:15], v[134:135], v[118:119]
	ds_bpermute_b32 v111, v95, v111
	v_pk_fma_f32 v[116:117], v[48:49], v[136:137], v[116:117]
	v_pk_fma_f32 v[118:119], v[16:17], v[136:137], v[118:119]
	s_waitcnt lgkmcnt(3)
	v_pk_fma_f32 v[116:117], v[42:43], v[112:113], v[116:117]
	v_pk_fma_f32 v[112:113], v[76:77], v[112:113], v[118:119]
	v_pk_fma_f32 v[116:117], v[44:45], v[114:115], v[116:117]
	v_pk_fma_f32 v[112:113], v[74:75], v[114:115], v[112:113]
	s_waitcnt lgkmcnt(2)
	v_pk_fma_f32 v[114:115], v[38:39], v[138:139], v[116:117]
	v_pk_fma_f32 v[112:113], v[80:81], v[138:139], v[112:113]
	v_cndmask_b32_e32 v101, v146, v202, vcc
	v_pk_fma_f32 v[114:115], v[40:41], v[140:141], v[114:115]
	v_pk_fma_f32 v[112:113], v[78:79], v[140:141], v[112:113]
	s_waitcnt lgkmcnt(0)
	v_add_f32_e32 v101, v101, v111
	v_pk_fma_f32 v[114:115], v[34:35], v[142:143], v[114:115]
	v_pk_fma_f32 v[112:113], v[2:3], v[142:143], v[112:113]
	v_cndmask_b32_e64 v146, v101, v172, s[8:9]
	v_cndmask_b32_e64 v101, v172, v101, s[8:9]
	v_pk_fma_f32 v[114:115], v[36:37], v[144:145], v[114:115]
	v_pk_fma_f32 v[112:113], v[4:5], v[144:145], v[112:113]
	ds_bpermute_b32 v147, v94, v101
	v_add_f32_e32 v136, v114, v115
	v_add_f32_e32 v101, v112, v113
	ds_read_b128 v[112:115], v103
	ds_read_b128 v[116:119], v104
	ds_read_b128 v[120:123], v105
	ds_read_b128 v[124:127], v106
	ds_read_b128 v[104:107], v107
	ds_read_b128 v[128:131], v108
	ds_read_b128 v[132:135], v109
	ds_read_b128 v[108:111], v110
	s_waitcnt lgkmcnt(7)
	v_pk_fma_f32 v[64:65], v[64:65], v[112:113], 0 op_sel_hi:[1,1,0]
	v_pk_fma_f32 v[30:31], v[30:31], v[112:113], 0 op_sel_hi:[1,1,0]
	v_pk_fma_f32 v[62:63], v[62:63], v[114:115], v[64:65]
	v_pk_fma_f32 v[30:31], v[32:33], v[114:115], v[30:31]
	s_waitcnt lgkmcnt(6)
	v_pk_fma_f32 v[32:33], v[68:69], v[116:117], v[62:63]
	v_pk_fma_f32 v[26:27], v[26:27], v[116:117], v[30:31]
	v_pk_fma_f32 v[30:31], v[66:67], v[118:119], v[32:33]
	v_pk_fma_f32 v[26:27], v[28:29], v[118:119], v[26:27]
	s_waitcnt lgkmcnt(5)
	v_pk_fma_f32 v[28:29], v[72:73], v[120:121], v[30:31]
	v_pk_fma_f32 v[22:23], v[22:23], v[120:121], v[26:27]
	v_pk_fma_f32 v[26:27], v[70:71], v[122:123], v[28:29]
	v_pk_fma_f32 v[22:23], v[24:25], v[122:123], v[22:23]
	s_waitcnt lgkmcnt(4)
	v_pk_fma_f32 v[24:25], v[50:51], v[124:125], v[26:27]
	v_pk_fma_f32 v[18:19], v[18:19], v[124:125], v[22:23]
	v_pk_fma_f32 v[22:23], v[52:53], v[126:127], v[24:25]
	v_pk_fma_f32 v[18:19], v[20:21], v[126:127], v[18:19]
	s_waitcnt lgkmcnt(3)
	v_pk_fma_f32 v[20:21], v[46:47], v[104:105], v[22:23]
	v_pk_fma_f32 v[14:15], v[14:15], v[104:105], v[18:19]
	v_pk_fma_f32 v[18:19], v[48:49], v[106:107], v[20:21]
	v_pk_fma_f32 v[14:15], v[16:17], v[106:107], v[14:15]
	s_waitcnt lgkmcnt(2)
	v_pk_fma_f32 v[16:17], v[42:43], v[128:129], v[18:19]
	v_pk_fma_f32 v[14:15], v[76:77], v[128:129], v[14:15]
	v_pk_fma_f32 v[16:17], v[44:45], v[130:131], v[16:17]
	v_pk_fma_f32 v[14:15], v[74:75], v[130:131], v[14:15]
	s_waitcnt lgkmcnt(1)
	v_pk_fma_f32 v[16:17], v[38:39], v[132:133], v[16:17]
	v_pk_fma_f32 v[14:15], v[80:81], v[132:133], v[14:15]
	v_pk_fma_f32 v[16:17], v[40:41], v[134:135], v[16:17]
	v_pk_fma_f32 v[14:15], v[78:79], v[134:135], v[14:15]
	s_waitcnt lgkmcnt(0)
	v_pk_fma_f32 v[16:17], v[34:35], v[108:109], v[16:17]
	v_pk_fma_f32 v[2:3], v[2:3], v[108:109], v[14:15]
	v_cndmask_b32_e32 v103, v136, v203, vcc
	v_cndmask_b32_e32 v136, v203, v136, vcc
	v_pk_fma_f32 v[14:15], v[36:37], v[110:111], v[16:17]
	v_pk_fma_f32 v[2:3], v[4:5], v[110:111], v[2:3]
	ds_bpermute_b32 v136, v95, v136
	v_add_f32_e32 v5, v14, v15
	v_add_f32_e32 v4, v2, v3
	v_and_b32_e32 v102, 8, v60
	v_cndmask_b32_e32 v2, v204, v5, vcc
	ds_bpermute_b32 v3, v95, v2
	s_waitcnt lgkmcnt(1)
	v_add_f32_e32 v30, v103, v136
	v_cndmask_b32_e64 v28, v168, v30, s[8:9]
	v_cndmask_b32_e32 v5, v5, v204, vcc
	ds_bpermute_b32 v26, v94, v28
	s_waitcnt lgkmcnt(1)
	v_add_f32_e32 v15, v5, v3
	v_cndmask_b32_e64 v3, v158, v15, s[8:9]
	ds_bpermute_b32 v16, v94, v3
	v_cndmask_b32_e64 v14, v30, v168, s[8:9]
	s_waitcnt lgkmcnt(1)
	v_add_f32_e32 v14, v14, v26
	v_cmp_eq_u32_e64 s[10:11], 0, v102
	v_add_f32_e32 v2, v146, v147
	v_and_b32_e32 v17, 4, v60
	v_cndmask_b32_e64 v3, v14, v150, s[10:11]
	v_cndmask_b32_e64 v5, v150, v14, s[10:11]
	v_cndmask_b32_e64 v14, v15, v158, s[8:9]
	s_waitcnt lgkmcnt(0)
	v_add_f32_e32 v14, v14, v16
	v_cndmask_b32_e64 v15, v2, v14, s[10:11]
	ds_bpermute_b32 v5, v93, v5
	ds_bpermute_b32 v15, v93, v15
	v_cndmask_b32_e64 v2, v14, v2, s[10:11]
	v_cmp_eq_u32_e64 s[12:13], 0, v17
	v_lshlrev_b32_e32 v16, 2, v96
	s_waitcnt lgkmcnt(1)
	v_add_f32_e32 v3, v3, v5
	s_waitcnt lgkmcnt(0)
	v_add_f32_e32 v2, v2, v15
	v_cndmask_b32_e64 v14, v2, v3, s[12:13]
	v_cndmask_b32_e64 v2, v3, v2, s[12:13]
	ds_bpermute_b32 v2, v16, v2
	v_cndmask_b32_e64 v3, v55, v90, s[14:15]
	v_lshlrev_b32_e32 v5, 2, v3
	v_cmp_lt_i32_e64 s[14:15], v91, v86
	s_waitcnt lgkmcnt(0)
	v_add_f32_e32 v2, v14, v2
	ds_bpermute_b32 v3, v5, v2
	v_cndmask_b32_e64 v14, v55, v91, s[14:15]
	v_lshlrev_b32_e32 v15, 2, v14
	v_and_b32_e32 v14, 3, v60
	v_cmp_eq_u32_e64 s[14:15], 0, v14
	s_waitcnt lgkmcnt(0)
	v_add_f32_e32 v2, v2, v3
	ds_bpermute_b32 v3, v15, v2
	v_bfe_u32 v14, v60, 2, 4
	v_lshlrev_b32_e32 v60, 2, v14
	s_and_saveexec_b64 s[52:53], s[14:15]
	s_cbranch_execz .LBB0_86
	global_load_dword v17, v60, s[50:51]
	s_waitcnt lgkmcnt(0)
	v_add_f32_e32 v2, v2, v3
	v_cmp_lt_u32_e64 s[16:17], 7, v14
	s_waitcnt vmcnt(0)
	v_add_f32_e32 v17, v2, v17
	s_and_saveexec_b64 s[18:19], s[16:17]
	s_xor_b64 s[54:55], exec, s[18:19]
	s_cbranch_execz .LBB0_83
	v_mul_f32_e64 v2, |v17|, s66
	v_exp_f32_e32 v18, v2
	s_lshl_b64 s[16:17], s[40:41], 5
	s_add_u32 s16, s58, s16
	s_addc_u32 s17, s59, s17
	v_add_f32_e32 v18, 1.0, v18
	v_lshl_add_u64 v[2:3], s[16:17], 0, v[60:61]
	v_cmp_gt_f32_e64 s[16:17], s67, v18
	v_max_f32_e32 v17, v17, v17
	v_min_f32_e32 v17, 0, v17
	v_cndmask_b32_e64 v19, 0, 32, s[16:17]
	v_ldexp_f32 v18, v18, v19
	v_log_f32_e32 v18, v18
	v_lshl_add_u64 v[2:3], v[2:3], 0, s[38:39]
	v_mul_f32_e32 v19, 0x3f317217, v18
	v_fma_f32 v19, v18, s68, -v19
	v_fmac_f32_e32 v19, 0x3377d1cf, v18
	v_fmac_f32_e32 v19, 0x3f317217, v18
	v_cmp_lt_f32_e64 s[18:19], |v18|, s69
	s_nop 1
	v_cndmask_b32_e64 v18, v18, v19, s[18:19]
	v_cndmask_b32_e64 v19, 0, v92, s[16:17]
	v_sub_f32_e32 v18, v18, v19
	v_sub_f32_e32 v17, v17, v18

.LBB0_96:
	s_abs_i32 s21, s53
	s_mul_hi_u32 s30, s21, s39
	s_mul_i32 s31, s30, s38
	s_ashr_i32 s20, s53, 31
	s_sub_i32 s21, s21, s31
	s_xor_b32 s20, s20, s43
	s_add_i32 s31, s30, 1
	s_sub_i32 s34, s21, s38
	s_cmp_ge_u32 s21, s38
	s_cselect_b32 s30, s31, s30
	s_cselect_b32 s21, s34, s21
	s_add_i32 s31, s30, 1
	s_cmp_ge_u32 s21, s38
	s_cselect_b32 s21, s31, s30
	s_xor_b32 s21, s21, s20
	s_sub_i32 s20, s21, s20
	s_add_i32 s20, s53, s20
	s_and_b32 s20, s20, 7
	v_readlane_b32 s21, v253, 15
	s_cmp_lg_u32 s21, s20
	s_cbranch_scc1 .LBB0_95
	s_lshr_b32 s21, s53, 3
	s_add_i32 s20, s53, 0x2000
	s_add_i32 s21, s21, 1
	s_cmp_gt_i32 s53, -1
	s_cselect_b32 s21, s21, 0
	s_mul_hi_u32 s30, s21, 0xc000
	s_mul_i32 s21, s21, 0xc000
	s_add_u32 s34, s24, s21
	s_addc_u32 s35, s25, s30
	s_waitcnt lgkmcnt(0)
	v_add_co_u32_e32 v2, vcc, 0xfffff000, v32
	v_lshl_add_u64 v[46:47], v[54:55], 2, s[34:35]
	s_nop 0
	v_addc_co_u32_e32 v3, vcc, -1, v33, vcc
	v_add_co_u32_e32 v42, vcc, s41, v46
	global_load_dwordx4 v[36:39], v[2:3], off offset:-3072
	global_load_dwordx4 v[120:123], v[2:3], off offset:-2048
	global_load_dwordx4 v[22:25], v[2:3], off offset:-1024
	global_load_dwordx4 v[18:21], v[32:33], off offset:-4096
	global_load_dwordx4 v[14:17], v[32:33], off offset:-3072
	global_load_dwordx4 v[10:13], v[32:33], off offset:-2048
	global_load_dwordx4 v[6:9], v[32:33], off offset:-1024
	s_nop 0
	global_load_dwordx4 v[2:5], v[32:33], off
	v_addc_co_u32_e32 v43, vcc, 0, v47, vcc
	global_load_dwordx4 v[124:127], v[42:43], off offset:-4096
	global_load_dwordx4 v[128:131], v[46:47], off
	s_ashr_i32 s21, s20, 31
	s_lshl_b64 s[30:31], s[20:21], 12
	v_lshl_add_u64 v[44:45], v[30:31], 0, s[30:31]
	v_lshl_add_u64 v[48:49], v[46:47], 0, s[26:27]
	s_waitcnt vmcnt(1)
	v_pk_add_f32 v[40:41], v[124:125], 1.0 op_sel_hi:[1,0]
	v_pk_add_f32 v[34:35], v[126:127], 1.0 op_sel_hi:[1,0]
	s_waitcnt vmcnt(0)
	v_pk_fma_f32 v[36:37], v[36:37], v[40:41], v[128:129]
	v_pk_fma_f32 v[34:35], v[38:39], v[34:35], v[130:131]
	v_cvt_pk_bf16_f32 v38, v36, v37
	v_cvt_pk_bf16_f32 v39, v34, v35
	global_store_dwordx2 v[44:45], v[38:39], off
	global_load_dwordx4 v[38:41], v[48:49], off offset:1024
	s_nop 0
	global_load_dwordx4 v[124:127], v[46:47], off offset:1024
	s_waitcnt vmcnt(1)
	v_pk_add_f32 v[40:41], v[40:41], 1.0 op_sel_hi:[1,0]
	v_pk_add_f32 v[128:129], v[38:39], 1.0 op_sel_hi:[1,0]
	s_waitcnt vmcnt(0)
	v_pk_fma_f32 v[38:39], v[122:123], v[40:41], v[126:127]
	v_pk_fma_f32 v[40:41], v[120:121], v[128:129], v[124:125]
	v_cvt_pk_bf16_f32 v120, v40, v41
	v_cvt_pk_bf16_f32 v121, v38, v39
	global_store_dwordx2 v[44:45], v[120:121], off offset:512
	global_load_dwordx4 v[120:123], v[48:49], off offset:2048
	s_nop 0
	global_load_dwordx4 v[124:127], v[46:47], off offset:2048
	s_waitcnt vmcnt(1)
	v_pk_add_f32 v[120:121], v[120:121], 1.0 op_sel_hi:[1,0]
	s_waitcnt vmcnt(0)
	v_pk_fma_f32 v[22:23], v[22:23], v[120:121], v[124:125]
	v_pk_add_f32 v[122:123], v[122:123], 1.0 op_sel_hi:[1,0]
	s_nop 0
	v_pk_fma_f32 v[24:25], v[24:25], v[122:123], v[126:127]
	v_cvt_pk_bf16_f32 v120, v22, v23
	v_cvt_pk_bf16_f32 v121, v24, v25
	global_store_dwordx2 v[44:45], v[120:121], off offset:1024
	global_load_dwordx4 v[120:123], v[48:49], off offset:3072
	s_nop 0
	global_load_dwordx4 v[124:127], v[46:47], off offset:3072
	s_waitcnt vmcnt(1)
	v_pk_add_f32 v[120:121], v[120:121], 1.0 op_sel_hi:[1,0]
	v_pk_add_f32 v[48:49], v[122:123], 1.0 op_sel_hi:[1,0]
	s_waitcnt vmcnt(0)
	v_pk_fma_f32 v[18:19], v[18:19], v[120:121], v[124:125]
	v_pk_fma_f32 v[20:21], v[20:21], v[48:49], v[126:127]
	v_cvt_pk_bf16_f32 v48, v18, v19
	v_cvt_pk_bf16_f32 v49, v20, v21
	global_store_dwordx2 v[44:45], v[48:49], off offset:1536
	v_add_co_u32_e32 v124, vcc, s48, v46
	global_load_dwordx4 v[120:123], v[42:43], off
	s_nop 0
	v_addc_co_u32_e32 v125, vcc, 0, v47, vcc
	global_load_dwordx4 v[46:49], v[124:125], off
	s_waitcnt vmcnt(1)
	v_pk_add_f32 v[120:121], v[120:121], 1.0 op_sel_hi:[1,0]
	v_pk_add_f32 v[122:123], v[122:123], 1.0 op_sel_hi:[1,0]
	s_waitcnt vmcnt(0)
	v_pk_fma_f32 v[14:15], v[14:15], v[120:121], v[46:47]
	s_nop 0
	v_pk_fma_f32 v[16:17], v[16:17], v[122:123], v[48:49]
	v_cvt_pk_bf16_f32 v46, v14, v15
	v_cvt_pk_bf16_f32 v47, v16, v17
	global_store_dwordx2 v[44:45], v[46:47], off offset:2048
	global_load_dwordx4 v[46:49], v[42:43], off offset:1024
	s_nop 0
	global_load_dwordx4 v[120:123], v[124:125], off offset:1024
	s_waitcnt vmcnt(1)
	v_pk_add_f32 v[46:47], v[46:47], 1.0 op_sel_hi:[1,0]
	s_waitcnt vmcnt(0)
	v_pk_fma_f32 v[10:11], v[10:11], v[46:47], v[120:121]
	v_pk_add_f32 v[48:49], v[48:49], 1.0 op_sel_hi:[1,0]
	s_nop 0
	v_pk_fma_f32 v[12:13], v[12:13], v[48:49], v[122:123]
	v_cvt_pk_bf16_f32 v46, v10, v11
	v_cvt_pk_bf16_f32 v47, v12, v13
	global_store_dwordx2 v[44:45], v[46:47], off offset:2560
	global_load_dwordx4 v[46:49], v[42:43], off offset:2048
	s_nop 0
	global_load_dwordx4 v[120:123], v[124:125], off offset:2048
	s_waitcnt vmcnt(1)
	v_pk_add_f32 v[46:47], v[46:47], 1.0 op_sel_hi:[1,0]
	s_waitcnt vmcnt(0)
	v_pk_fma_f32 v[6:7], v[6:7], v[46:47], v[120:121]
	v_pk_add_f32 v[48:49], v[48:49], 1.0 op_sel_hi:[1,0]
	s_nop 0
	v_pk_fma_f32 v[8:9], v[8:9], v[48:49], v[122:123]
	v_cvt_pk_bf16_f32 v46, v6, v7
	v_cvt_pk_bf16_f32 v47, v8, v9
	global_store_dwordx2 v[44:45], v[46:47], off offset:3072
	global_load_dwordx4 v[46:49], v[42:43], off offset:3072
	s_nop 0
	global_load_dwordx4 v[120:123], v[124:125], off offset:3072
	s_waitcnt vmcnt(1)
	v_pk_add_f32 v[46:47], v[46:47], 1.0 op_sel_hi:[1,0]
	v_pk_add_f32 v[42:43], v[48:49], 1.0 op_sel_hi:[1,0]
	s_waitcnt vmcnt(0)
	v_pk_fma_f32 v[2:3], v[2:3], v[46:47], v[120:121]
	v_pk_fma_f32 v[4:5], v[4:5], v[42:43], v[122:123]
	v_cvt_pk_bf16_f32 v42, v2, v3
	v_cvt_pk_bf16_f32 v43, v4, v5
	global_store_dwordx2 v[44:45], v[42:43], off offset:3584
	ds_read_b128 v[42:45], v50
	s_waitcnt lgkmcnt(0)
	v_pk_fma_f32 v[42:43], v[36:37], v[42:43], 0 op_sel_hi:[1,1,0]
	s_nop 0
	v_pk_fma_f32 v[46:47], v[34:35], v[44:45], v[42:43]
	ds_read_b128 v[42:45], v50 offset:1024
	s_waitcnt lgkmcnt(0)
	v_pk_fma_f32 v[42:43], v[40:41], v[42:43], v[46:47]
	s_nop 0
	v_pk_fma_f32 v[46:47], v[38:39], v[44:45], v[42:43]
	ds_read_b128 v[42:45], v50 offset:2048
	s_waitcnt lgkmcnt(0)
	v_pk_fma_f32 v[42:43], v[22:23], v[42:43], v[46:47]
	s_nop 0
	v_pk_fma_f32 v[46:47], v[24:25], v[44:45], v[42:43]
	ds_read_b128 v[42:45], v50 offset:3072
	s_waitcnt lgkmcnt(0)
	v_pk_fma_f32 v[42:43], v[18:19], v[42:43], v[46:47]
	s_nop 0
	v_pk_fma_f32 v[46:47], v[20:21], v[44:45], v[42:43]
	ds_read_b128 v[42:45], v50 offset:4096
	s_waitcnt lgkmcnt(0)
	v_pk_fma_f32 v[42:43], v[14:15], v[42:43], v[46:47]
	s_nop 0
	v_pk_fma_f32 v[46:47], v[16:17], v[44:45], v[42:43]
	ds_read_b128 v[42:45], v50 offset:5120
	s_waitcnt lgkmcnt(0)
	v_pk_fma_f32 v[42:43], v[10:11], v[42:43], v[46:47]
	s_nop 0
	v_pk_fma_f32 v[46:47], v[12:13], v[44:45], v[42:43]
	ds_read_b128 v[42:45], v50 offset:6144
	s_waitcnt lgkmcnt(0)
	v_pk_fma_f32 v[42:43], v[6:7], v[42:43], v[46:47]
	s_nop 0
	v_pk_fma_f32 v[46:47], v[8:9], v[44:45], v[42:43]
	ds_read_b128 v[42:45], v50 offset:7168
	s_waitcnt lgkmcnt(0)
	v_pk_fma_f32 v[42:43], v[2:3], v[42:43], v[46:47]
	s_nop 0
	v_pk_fma_f32 v[42:43], v[4:5], v[44:45], v[42:43]
	ds_read_b128 v[44:47], v50 offset:8192
	v_add_f32_e32 v42, v42, v43
	s_waitcnt lgkmcnt(0)
	v_pk_fma_f32 v[44:45], v[36:37], v[44:45], 0 op_sel_hi:[1,1,0]
	s_nop 0
	v_pk_fma_f32 v[48:49], v[34:35], v[46:47], v[44:45]
	ds_read_b128 v[44:47], v50 offset:9216
	s_waitcnt lgkmcnt(0)
	v_pk_fma_f32 v[44:45], v[40:41], v[44:45], v[48:49]
	s_nop 0
	v_pk_fma_f32 v[48:49], v[38:39], v[46:47], v[44:45]
	ds_read_b128 v[44:47], v50 offset:10240
	s_waitcnt lgkmcnt(0)
	v_pk_fma_f32 v[44:45], v[22:23], v[44:45], v[48:49]
	s_nop 0
	v_pk_fma_f32 v[48:49], v[24:25], v[46:47], v[44:45]
	ds_read_b128 v[44:47], v50 offset:11264
	s_waitcnt lgkmcnt(0)
	v_pk_fma_f32 v[44:45], v[18:19], v[44:45], v[48:49]
	s_nop 0
	v_pk_fma_f32 v[48:49], v[20:21], v[46:47], v[44:45]
	ds_read_b128 v[44:47], v50 offset:12288
	s_waitcnt lgkmcnt(0)
	v_pk_fma_f32 v[44:45], v[14:15], v[44:45], v[48:49]
	s_nop 0
	v_pk_fma_f32 v[48:49], v[16:17], v[46:47], v[44:45]
	ds_read_b128 v[44:47], v50 offset:13312
	s_waitcnt lgkmcnt(0)
	v_pk_fma_f32 v[44:45], v[10:11], v[44:45], v[48:49]
	s_nop 0
	v_pk_fma_f32 v[48:49], v[12:13], v[46:47], v[44:45]
	ds_read_b128 v[44:47], v50 offset:14336
	s_waitcnt lgkmcnt(0)
	v_pk_fma_f32 v[44:45], v[6:7], v[44:45], v[48:49]
	s_nop 0
	v_pk_fma_f32 v[48:49], v[8:9], v[46:47], v[44:45]
	ds_read_b128 v[44:47], v50 offset:15360
	s_waitcnt lgkmcnt(0)
	v_pk_fma_f32 v[44:45], v[2:3], v[44:45], v[48:49]
	s_nop 0
	v_pk_fma_f32 v[44:45], v[4:5], v[46:47], v[44:45]
	s_nop 0
	v_add_f32_e32 v43, v44, v45
	ds_read_b128 v[44:47], v50 offset:16384
	s_waitcnt lgkmcnt(0)
	v_pk_fma_f32 v[44:45], v[36:37], v[44:45], 0 op_sel_hi:[1,1,0]
	s_nop 0
	v_pk_fma_f32 v[48:49], v[34:35], v[46:47], v[44:45]
	ds_read_b128 v[44:47], v50 offset:17408
	s_waitcnt lgkmcnt(0)
	v_pk_fma_f32 v[44:45], v[40:41], v[44:45], v[48:49]
	s_nop 0
	v_pk_fma_f32 v[48:49], v[38:39], v[46:47], v[44:45]
	ds_read_b128 v[44:47], v50 offset:18432
	s_waitcnt lgkmcnt(0)
	v_pk_fma_f32 v[44:45], v[22:23], v[44:45], v[48:49]
	s_nop 0
	v_pk_fma_f32 v[48:49], v[24:25], v[46:47], v[44:45]
	ds_read_b128 v[44:47], v50 offset:19456
	s_waitcnt lgkmcnt(0)
	v_pk_fma_f32 v[44:45], v[18:19], v[44:45], v[48:49]
	s_nop 0
	v_pk_fma_f32 v[48:49], v[20:21], v[46:47], v[44:45]
	ds_read_b128 v[44:47], v50 offset:20480
	s_waitcnt lgkmcnt(0)
	v_pk_fma_f32 v[44:45], v[14:15], v[44:45], v[48:49]
	s_nop 0
	v_pk_fma_f32 v[48:49], v[16:17], v[46:47], v[44:45]
	ds_read_b128 v[44:47], v50 offset:21504
	s_waitcnt lgkmcnt(0)
	v_pk_fma_f32 v[44:45], v[10:11], v[44:45], v[48:49]
	s_nop 0
	v_pk_fma_f32 v[48:49], v[12:13], v[46:47], v[44:45]
	ds_read_b128 v[44:47], v50 offset:22528
	s_waitcnt lgkmcnt(0)
	v_pk_fma_f32 v[44:45], v[6:7], v[44:45], v[48:49]
	s_nop 0
	v_pk_fma_f32 v[48:49], v[8:9], v[46:47], v[44:45]
	ds_read_b128 v[44:47], v50 offset:23552
	s_waitcnt lgkmcnt(0)
	v_pk_fma_f32 v[44:45], v[2:3], v[44:45], v[48:49]
	s_nop 0
	v_pk_fma_f32 v[44:45], v[4:5], v[46:47], v[44:45]
	ds_read_b128 v[46:49], v50 offset:24576
	v_add_f32_e32 v44, v44, v45
	s_waitcnt lgkmcnt(0)
	v_pk_fma_f32 v[46:47], v[36:37], v[46:47], 0 op_sel_hi:[1,1,0]
	s_nop 0
	v_pk_fma_f32 v[120:121], v[34:35], v[48:49], v[46:47]
	ds_read_b128 v[46:49], v50 offset:25600
	s_waitcnt lgkmcnt(0)
	v_pk_fma_f32 v[46:47], v[40:41], v[46:47], v[120:121]
	s_nop 0
	v_pk_fma_f32 v[120:121], v[38:39], v[48:49], v[46:47]
	ds_read_b128 v[46:49], v50 offset:26624
	s_waitcnt lgkmcnt(0)
	v_pk_fma_f32 v[46:47], v[22:23], v[46:47], v[120:121]
	s_nop 0
	v_pk_fma_f32 v[120:121], v[24:25], v[48:49], v[46:47]
	ds_read_b128 v[46:49], v50 offset:27648
	s_waitcnt lgkmcnt(0)
	v_pk_fma_f32 v[46:47], v[18:19], v[46:47], v[120:121]
	s_nop 0
	v_pk_fma_f32 v[120:121], v[20:21], v[48:49], v[46:47]
	ds_read_b128 v[46:49], v50 offset:28672
	s_waitcnt lgkmcnt(0)
	v_pk_fma_f32 v[46:47], v[14:15], v[46:47], v[120:121]
	s_nop 0
	v_pk_fma_f32 v[120:121], v[16:17], v[48:49], v[46:47]
	ds_read_b128 v[46:49], v50 offset:29696
	s_waitcnt lgkmcnt(0)
	v_pk_fma_f32 v[46:47], v[10:11], v[46:47], v[120:121]
	s_nop 0
	v_pk_fma_f32 v[120:121], v[12:13], v[48:49], v[46:47]
	ds_read_b128 v[46:49], v50 offset:30720
	s_waitcnt lgkmcnt(0)
	v_pk_fma_f32 v[46:47], v[6:7], v[46:47], v[120:121]
	s_nop 0
	v_pk_fma_f32 v[120:121], v[8:9], v[48:49], v[46:47]
	ds_read_b128 v[46:49], v50 offset:31744
	s_waitcnt lgkmcnt(0)
	v_pk_fma_f32 v[46:47], v[2:3], v[46:47], v[120:121]
	s_nop 0
	v_pk_fma_f32 v[46:47], v[4:5], v[48:49], v[46:47]
	s_nop 0
	v_add_f32_e32 v45, v46, v47
	ds_read_b128 v[46:49], v50 offset:32768
	s_waitcnt lgkmcnt(0)
	v_pk_fma_f32 v[46:47], v[36:37], v[46:47], 0 op_sel_hi:[1,1,0]
	s_nop 0
	v_pk_fma_f32 v[120:121], v[34:35], v[48:49], v[46:47]
	ds_read_b128 v[46:49], v50 offset:33792
	s_waitcnt lgkmcnt(0)
	v_pk_fma_f32 v[46:47], v[40:41], v[46:47], v[120:121]
	s_nop 0
	v_pk_fma_f32 v[120:121], v[38:39], v[48:49], v[46:47]
	ds_read_b128 v[46:49], v50 offset:34816
	s_waitcnt lgkmcnt(0)
	v_pk_fma_f32 v[46:47], v[22:23], v[46:47], v[120:121]
	s_nop 0
	v_pk_fma_f32 v[120:121], v[24:25], v[48:49], v[46:47]
	ds_read_b128 v[46:49], v50 offset:35840
	s_waitcnt lgkmcnt(0)
	v_pk_fma_f32 v[46:47], v[18:19], v[46:47], v[120:121]
	s_nop 0
	v_pk_fma_f32 v[120:121], v[20:21], v[48:49], v[46:47]
	ds_read_b128 v[46:49], v50 offset:36864
	s_waitcnt lgkmcnt(0)
	v_pk_fma_f32 v[46:47], v[14:15], v[46:47], v[120:121]
	s_nop 0
	v_pk_fma_f32 v[120:121], v[16:17], v[48:49], v[46:47]
	ds_read_b128 v[46:49], v50 offset:37888
	s_waitcnt lgkmcnt(0)
	v_pk_fma_f32 v[46:47], v[10:11], v[46:47], v[120:121]
	s_nop 0
	v_pk_fma_f32 v[120:121], v[12:13], v[48:49], v[46:47]
	ds_read_b128 v[46:49], v50 offset:38912
	s_waitcnt lgkmcnt(0)
	v_pk_fma_f32 v[46:47], v[6:7], v[46:47], v[120:121]
	s_nop 0
	v_pk_fma_f32 v[120:121], v[8:9], v[48:49], v[46:47]
	ds_read_b128 v[46:49], v50 offset:39936
	s_waitcnt lgkmcnt(0)
	v_pk_fma_f32 v[46:47], v[2:3], v[46:47], v[120:121]
	ds_read_b128 v[120:123], v50 offset:40960
	v_pk_fma_f32 v[46:47], v[4:5], v[48:49], v[46:47]
	s_waitcnt lgkmcnt(0)
	v_pk_fma_f32 v[48:49], v[36:37], v[120:121], 0 op_sel_hi:[1,1,0]
	s_nop 0
	v_pk_fma_f32 v[48:49], v[34:35], v[122:123], v[48:49]
	ds_read_b128 v[120:123], v50 offset:41984
	v_add_f32_e32 v46, v46, v47
	s_waitcnt lgkmcnt(0)
	v_pk_fma_f32 v[48:49], v[40:41], v[120:121], v[48:49]
	s_nop 0
	v_pk_fma_f32 v[48:49], v[38:39], v[122:123], v[48:49]
	ds_read_b128 v[120:123], v50 offset:43008
	s_waitcnt lgkmcnt(0)
	v_pk_fma_f32 v[48:49], v[22:23], v[120:121], v[48:49]
	s_nop 0
	v_pk_fma_f32 v[48:49], v[24:25], v[122:123], v[48:49]
	ds_read_b128 v[120:123], v50 offset:44032
	s_waitcnt lgkmcnt(0)
	v_pk_fma_f32 v[48:49], v[18:19], v[120:121], v[48:49]
	s_nop 0
	v_pk_fma_f32 v[48:49], v[20:21], v[122:123], v[48:49]
	ds_read_b128 v[120:123], v50 offset:45056
	s_waitcnt lgkmcnt(0)
	v_pk_fma_f32 v[48:49], v[14:15], v[120:121], v[48:49]
	s_nop 0
	v_pk_fma_f32 v[48:49], v[16:17], v[122:123], v[48:49]
	ds_read_b128 v[120:123], v50 offset:46080
	s_waitcnt lgkmcnt(0)
	v_pk_fma_f32 v[48:49], v[10:11], v[120:121], v[48:49]
	s_nop 0
	v_pk_fma_f32 v[48:49], v[12:13], v[122:123], v[48:49]
	ds_read_b128 v[120:123], v50 offset:47104
	s_waitcnt lgkmcnt(0)
	v_pk_fma_f32 v[48:49], v[6:7], v[120:121], v[48:49]
	s_nop 0
	v_pk_fma_f32 v[48:49], v[8:9], v[122:123], v[48:49]
	ds_read_b128 v[120:123], v50 offset:48128
	s_waitcnt lgkmcnt(0)
	v_pk_fma_f32 v[48:49], v[2:3], v[120:121], v[48:49]
	s_nop 0
	v_pk_fma_f32 v[48:49], v[4:5], v[122:123], v[48:49]
	ds_read_b128 v[120:123], v50 offset:49152
	v_add_f32_e32 v47, v48, v49
	s_waitcnt lgkmcnt(0)
	v_pk_fma_f32 v[48:49], v[36:37], v[120:121], 0 op_sel_hi:[1,1,0]
	s_nop 0
	v_pk_fma_f32 v[48:49], v[34:35], v[122:123], v[48:49]
	ds_read_b128 v[120:123], v50 offset:50176
	s_waitcnt lgkmcnt(0)
	v_pk_fma_f32 v[48:49], v[40:41], v[120:121], v[48:49]
	s_nop 0
	v_pk_fma_f32 v[48:49], v[38:39], v[122:123], v[48:49]
	ds_read_b128 v[120:123], v50 offset:51200
	s_waitcnt lgkmcnt(0)
	v_pk_fma_f32 v[48:49], v[22:23], v[120:121], v[48:49]
	s_nop 0
	v_pk_fma_f32 v[48:49], v[24:25], v[122:123], v[48:49]
	ds_read_b128 v[120:123], v50 offset:52224
	s_waitcnt lgkmcnt(0)
	v_pk_fma_f32 v[48:49], v[18:19], v[120:121], v[48:49]
	s_nop 0
	v_pk_fma_f32 v[48:49], v[20:21], v[122:123], v[48:49]
	ds_read_b128 v[120:123], v50 offset:53248
	s_waitcnt lgkmcnt(0)
	v_pk_fma_f32 v[48:49], v[14:15], v[120:121], v[48:49]
	s_nop 0
	v_pk_fma_f32 v[48:49], v[16:17], v[122:123], v[48:49]
	ds_read_b128 v[120:123], v50 offset:54272
	s_waitcnt lgkmcnt(0)
	v_pk_fma_f32 v[48:49], v[10:11], v[120:121], v[48:49]
	s_nop 0
	v_pk_fma_f32 v[48:49], v[12:13], v[122:123], v[48:49]
	ds_read_b128 v[120:123], v50 offset:55296
	s_waitcnt lgkmcnt(0)
	v_pk_fma_f32 v[48:49], v[6:7], v[120:121], v[48:49]
	s_nop 0
	v_pk_fma_f32 v[48:49], v[8:9], v[122:123], v[48:49]
	ds_read_b128 v[120:123], v50 offset:56320
	s_waitcnt lgkmcnt(0)
	v_pk_fma_f32 v[48:49], v[2:3], v[120:121], v[48:49]
	s_nop 0
	v_pk_fma_f32 v[48:49], v[4:5], v[122:123], v[48:49]
	ds_read_b128 v[120:123], v50 offset:57344
	v_add_f32_e32 v48, v48, v49
	s_waitcnt lgkmcnt(0)
	v_pk_fma_f32 v[120:121], v[36:37], v[120:121], 0 op_sel_hi:[1,1,0]
	s_nop 0
	v_pk_fma_f32 v[124:125], v[34:35], v[122:123], v[120:121]
	ds_read_b128 v[120:123], v50 offset:58368
	s_waitcnt lgkmcnt(0)
	v_pk_fma_f32 v[120:121], v[40:41], v[120:121], v[124:125]
	s_nop 0
	v_pk_fma_f32 v[124:125], v[38:39], v[122:123], v[120:121]
	ds_read_b128 v[120:123], v50 offset:59392
	s_waitcnt lgkmcnt(0)
	v_pk_fma_f32 v[120:121], v[22:23], v[120:121], v[124:125]
	s_nop 0
	v_pk_fma_f32 v[124:125], v[24:25], v[122:123], v[120:121]
	ds_read_b128 v[120:123], v50 offset:60416
	s_waitcnt lgkmcnt(0)
	v_pk_fma_f32 v[120:121], v[18:19], v[120:121], v[124:125]
	s_nop 0
	v_pk_fma_f32 v[124:125], v[20:21], v[122:123], v[120:121]
	ds_read_b128 v[120:123], v50 offset:61440
	s_waitcnt lgkmcnt(0)
	v_pk_fma_f32 v[120:121], v[14:15], v[120:121], v[124:125]
	s_nop 0
	v_pk_fma_f32 v[124:125], v[16:17], v[122:123], v[120:121]
	ds_read_b128 v[120:123], v50 offset:62464
	s_waitcnt lgkmcnt(0)
	v_pk_fma_f32 v[120:121], v[10:11], v[120:121], v[124:125]
	s_nop 0
	v_pk_fma_f32 v[124:125], v[12:13], v[122:123], v[120:121]
	ds_read_b128 v[120:123], v50 offset:63488
	s_waitcnt lgkmcnt(0)
	v_pk_fma_f32 v[120:121], v[6:7], v[120:121], v[124:125]
	s_nop 0
	v_pk_fma_f32 v[124:125], v[8:9], v[122:123], v[120:121]
	ds_read_b128 v[120:123], v50 offset:64512
	s_waitcnt lgkmcnt(0)
	v_pk_fma_f32 v[120:121], v[2:3], v[120:121], v[124:125]
	s_nop 0
	v_pk_fma_f32 v[120:121], v[4:5], v[122:123], v[120:121]
	s_nop 0
	v_add_f32_e32 v49, v120, v121
	ds_read_b128 v[120:123], v51
	s_waitcnt lgkmcnt(0)
	v_pk_fma_f32 v[120:121], v[36:37], v[120:121], 0 op_sel_hi:[1,1,0]
	s_nop 0
	v_pk_fma_f32 v[124:125], v[34:35], v[122:123], v[120:121]
	ds_read_b128 v[120:123], v52
	s_waitcnt lgkmcnt(0)
	v_pk_fma_f32 v[120:121], v[40:41], v[120:121], v[124:125]
	s_nop 0
	v_pk_fma_f32 v[124:125], v[38:39], v[122:123], v[120:121]
	ds_read_b128 v[120:123], v53
	s_waitcnt lgkmcnt(0)
	v_pk_fma_f32 v[120:121], v[22:23], v[120:121], v[124:125]
	s_nop 0
	v_pk_fma_f32 v[124:125], v[24:25], v[122:123], v[120:121]
	ds_read_b128 v[120:123], v56
	s_waitcnt lgkmcnt(0)
	v_pk_fma_f32 v[120:121], v[18:19], v[120:121], v[124:125]
	s_nop 0
	v_pk_fma_f32 v[124:125], v[20:21], v[122:123], v[120:121]
	ds_read_b128 v[120:123], v57
	s_waitcnt lgkmcnt(0)
	v_pk_fma_f32 v[120:121], v[14:15], v[120:121], v[124:125]
	s_nop 0
	v_pk_fma_f32 v[124:125], v[16:17], v[122:123], v[120:121]
	ds_read_b128 v[120:123], v58
	s_waitcnt lgkmcnt(0)
	v_pk_fma_f32 v[120:121], v[10:11], v[120:121], v[124:125]
	s_nop 0
	v_pk_fma_f32 v[124:125], v[12:13], v[122:123], v[120:121]
	ds_read_b128 v[120:123], v59
	s_waitcnt lgkmcnt(0)
	v_pk_fma_f32 v[120:121], v[6:7], v[120:121], v[124:125]
	s_nop 0
	v_pk_fma_f32 v[124:125], v[8:9], v[122:123], v[120:121]
	ds_read_b128 v[120:123], v60
	s_waitcnt lgkmcnt(0)
	v_pk_fma_f32 v[120:121], v[2:3], v[120:121], v[124:125]
	s_nop 0
	v_pk_fma_f32 v[120:121], v[4:5], v[122:123], v[120:121]
	ds_read_b128 v[122:125], v61
	v_add_f32_e32 v120, v120, v121
	s_waitcnt lgkmcnt(0)
	v_pk_fma_f32 v[122:123], v[36:37], v[122:123], 0 op_sel_hi:[1,1,0]
	s_nop 0
	v_pk_fma_f32 v[126:127], v[34:35], v[124:125], v[122:123]
	ds_read_b128 v[122:125], v62
	s_waitcnt lgkmcnt(0)
	v_pk_fma_f32 v[122:123], v[40:41], v[122:123], v[126:127]
	s_nop 0
	v_pk_fma_f32 v[126:127], v[38:39], v[124:125], v[122:123]
	ds_read_b128 v[122:125], v63
	s_waitcnt lgkmcnt(0)
	v_pk_fma_f32 v[122:123], v[22:23], v[122:123], v[126:127]
	s_nop 0
	v_pk_fma_f32 v[126:127], v[24:25], v[124:125], v[122:123]
	ds_read_b128 v[122:125], v64
	s_waitcnt lgkmcnt(0)
	v_pk_fma_f32 v[122:123], v[18:19], v[122:123], v[126:127]
	s_nop 0
	v_pk_fma_f32 v[126:127], v[20:21], v[124:125], v[122:123]
	ds_read_b128 v[122:125], v65
	s_waitcnt lgkmcnt(0)
	v_pk_fma_f32 v[122:123], v[14:15], v[122:123], v[126:127]
	s_nop 0
	v_pk_fma_f32 v[126:127], v[16:17], v[124:125], v[122:123]
	ds_read_b128 v[122:125], v66
	s_waitcnt lgkmcnt(0)
	v_pk_fma_f32 v[122:123], v[10:11], v[122:123], v[126:127]
	s_nop 0
	v_pk_fma_f32 v[126:127], v[12:13], v[124:125], v[122:123]
	ds_read_b128 v[122:125], v67
	s_waitcnt lgkmcnt(0)
	v_pk_fma_f32 v[122:123], v[6:7], v[122:123], v[126:127]
	s_nop 0
	v_pk_fma_f32 v[126:127], v[8:9], v[124:125], v[122:123]
	ds_read_b128 v[122:125], v68
	s_waitcnt lgkmcnt(0)
	v_pk_fma_f32 v[122:123], v[2:3], v[122:123], v[126:127]
	s_nop 0
	v_pk_fma_f32 v[122:123], v[4:5], v[124:125], v[122:123]
	s_nop 0
	v_add_f32_e32 v121, v122, v123
	ds_read_b128 v[122:125], v69
	s_waitcnt lgkmcnt(0)
	v_pk_fma_f32 v[122:123], v[36:37], v[122:123], 0 op_sel_hi:[1,1,0]
	s_nop 0
	v_pk_fma_f32 v[126:127], v[34:35], v[124:125], v[122:123]
	ds_read_b128 v[122:125], v70
	s_waitcnt lgkmcnt(0)
	v_pk_fma_f32 v[122:123], v[40:41], v[122:123], v[126:127]
	s_nop 0
	v_pk_fma_f32 v[126:127], v[38:39], v[124:125], v[122:123]
	ds_read_b128 v[122:125], v71
	s_waitcnt lgkmcnt(0)
	v_pk_fma_f32 v[122:123], v[22:23], v[122:123], v[126:127]
	s_nop 0
	v_pk_fma_f32 v[126:127], v[24:25], v[124:125], v[122:123]
	ds_read_b128 v[122:125], v72
	s_waitcnt lgkmcnt(0)
	v_pk_fma_f32 v[122:123], v[18:19], v[122:123], v[126:127]
	s_nop 0
	v_pk_fma_f32 v[126:127], v[20:21], v[124:125], v[122:123]
	ds_read_b128 v[122:125], v73
	s_waitcnt lgkmcnt(0)
	v_pk_fma_f32 v[122:123], v[14:15], v[122:123], v[126:127]
	s_nop 0
	v_pk_fma_f32 v[126:127], v[16:17], v[124:125], v[122:123]
	ds_read_b128 v[122:125], v74
	s_waitcnt lgkmcnt(0)
	v_pk_fma_f32 v[122:123], v[10:11], v[122:123], v[126:127]
	s_nop 0
	v_pk_fma_f32 v[126:127], v[12:13], v[124:125], v[122:123]
	ds_read_b128 v[122:125], v75
	s_waitcnt lgkmcnt(0)
	v_pk_fma_f32 v[122:123], v[6:7], v[122:123], v[126:127]
	s_nop 0
	v_pk_fma_f32 v[126:127], v[8:9], v[124:125], v[122:123]
	ds_read_b128 v[122:125], v76
	s_waitcnt lgkmcnt(0)
	v_pk_fma_f32 v[122:123], v[2:3], v[122:123], v[126:127]
	s_nop 0
	v_pk_fma_f32 v[122:123], v[4:5], v[124:125], v[122:123]
	ds_read_b128 v[124:127], v77
	v_add_f32_e32 v122, v122, v123
	s_waitcnt lgkmcnt(0)
	v_pk_fma_f32 v[124:125], v[36:37], v[124:125], 0 op_sel_hi:[1,1,0]
	s_nop 0
	v_pk_fma_f32 v[128:129], v[34:35], v[126:127], v[124:125]
	ds_read_b128 v[124:127], v78
	s_waitcnt lgkmcnt(0)
	v_pk_fma_f32 v[124:125], v[40:41], v[124:125], v[128:129]
	s_nop 0
	v_pk_fma_f32 v[128:129], v[38:39], v[126:127], v[124:125]
	ds_read_b128 v[124:127], v79
	s_waitcnt lgkmcnt(0)
	v_pk_fma_f32 v[124:125], v[22:23], v[124:125], v[128:129]
	s_nop 0
	v_pk_fma_f32 v[128:129], v[24:25], v[126:127], v[124:125]
	ds_read_b128 v[124:127], v80
	s_waitcnt lgkmcnt(0)
	v_pk_fma_f32 v[124:125], v[18:19], v[124:125], v[128:129]
	s_nop 0
	v_pk_fma_f32 v[128:129], v[20:21], v[126:127], v[124:125]
	ds_read_b128 v[124:127], v81
	s_waitcnt lgkmcnt(0)
	v_pk_fma_f32 v[124:125], v[14:15], v[124:125], v[128:129]
	s_nop 0
	v_pk_fma_f32 v[128:129], v[16:17], v[126:127], v[124:125]
	ds_read_b128 v[124:127], v82
	s_waitcnt lgkmcnt(0)
	v_pk_fma_f32 v[124:125], v[10:11], v[124:125], v[128:129]
	s_nop 0
	v_pk_fma_f32 v[128:129], v[12:13], v[126:127], v[124:125]
	ds_read_b128 v[124:127], v83
	s_waitcnt lgkmcnt(0)
	v_pk_fma_f32 v[124:125], v[6:7], v[124:125], v[128:129]
	s_nop 0
	v_pk_fma_f32 v[128:129], v[8:9], v[126:127], v[124:125]
	ds_read_b128 v[124:127], v85
	s_waitcnt lgkmcnt(0)
	v_pk_fma_f32 v[124:125], v[2:3], v[124:125], v[128:129]
	s_nop 0
	v_pk_fma_f32 v[124:125], v[4:5], v[126:127], v[124:125]
	s_nop 0
	v_add_f32_e32 v123, v124, v125
	ds_read_b128 v[124:127], v86
	s_waitcnt lgkmcnt(0)
	v_pk_fma_f32 v[124:125], v[36:37], v[124:125], 0 op_sel_hi:[1,1,0]
	s_nop 0
	v_pk_fma_f32 v[128:129], v[34:35], v[126:127], v[124:125]
	ds_read_b128 v[124:127], v87
	s_waitcnt lgkmcnt(0)
	v_pk_fma_f32 v[124:125], v[40:41], v[124:125], v[128:129]
	s_nop 0
	v_pk_fma_f32 v[128:129], v[38:39], v[126:127], v[124:125]
	ds_read_b128 v[124:127], v88
	s_waitcnt lgkmcnt(0)
	v_pk_fma_f32 v[124:125], v[22:23], v[124:125], v[128:129]
	s_nop 0
	v_pk_fma_f32 v[128:129], v[24:25], v[126:127], v[124:125]
	ds_read_b128 v[124:127], v89
	s_waitcnt lgkmcnt(0)
	v_pk_fma_f32 v[124:125], v[18:19], v[124:125], v[128:129]
	s_nop 0
	v_pk_fma_f32 v[128:129], v[20:21], v[126:127], v[124:125]
	ds_read_b128 v[124:127], v90
	s_waitcnt lgkmcnt(0)
	v_pk_fma_f32 v[124:125], v[14:15], v[124:125], v[128:129]
	s_nop 0
	v_pk_fma_f32 v[128:129], v[16:17], v[126:127], v[124:125]
	ds_read_b128 v[124:127], v91
	s_waitcnt lgkmcnt(0)
	v_pk_fma_f32 v[124:125], v[10:11], v[124:125], v[128:129]
	s_nop 0
	v_pk_fma_f32 v[128:129], v[12:13], v[126:127], v[124:125]
	ds_read_b128 v[124:127], v92
	s_waitcnt lgkmcnt(0)
	v_pk_fma_f32 v[124:125], v[6:7], v[124:125], v[128:129]
	s_nop 0
	v_pk_fma_f32 v[128:129], v[8:9], v[126:127], v[124:125]
	ds_read_b128 v[124:127], v93
	s_waitcnt lgkmcnt(0)
	v_pk_fma_f32 v[124:125], v[2:3], v[124:125], v[128:129]
	s_nop 0
	v_pk_fma_f32 v[124:125], v[4:5], v[126:127], v[124:125]
	ds_read_b128 v[126:129], v94
	v_add_f32_e32 v124, v124, v125
	s_waitcnt lgkmcnt(0)
	v_pk_fma_f32 v[126:127], v[36:37], v[126:127], 0 op_sel_hi:[1,1,0]
	s_nop 0
	v_pk_fma_f32 v[130:131], v[34:35], v[128:129], v[126:127]
	ds_read_b128 v[126:129], v95
	s_waitcnt lgkmcnt(0)
	v_pk_fma_f32 v[126:127], v[40:41], v[126:127], v[130:131]
	s_nop 0
	v_pk_fma_f32 v[130:131], v[38:39], v[128:129], v[126:127]
	ds_read_b128 v[126:129], v96
	s_waitcnt lgkmcnt(0)
	v_pk_fma_f32 v[126:127], v[22:23], v[126:127], v[130:131]
	s_nop 0
	v_pk_fma_f32 v[130:131], v[24:25], v[128:129], v[126:127]
	ds_read_b128 v[126:129], v97
	s_waitcnt lgkmcnt(0)
	v_pk_fma_f32 v[126:127], v[18:19], v[126:127], v[130:131]
	s_nop 0
	v_pk_fma_f32 v[130:131], v[20:21], v[128:129], v[126:127]
	ds_read_b128 v[126:129], v98
	s_waitcnt lgkmcnt(0)
	v_pk_fma_f32 v[126:127], v[14:15], v[126:127], v[130:131]
	s_nop 0
	v_pk_fma_f32 v[130:131], v[16:17], v[128:129], v[126:127]
	ds_read_b128 v[126:129], v99
	s_waitcnt lgkmcnt(0)
	v_pk_fma_f32 v[126:127], v[10:11], v[126:127], v[130:131]
	s_nop 0
	v_pk_fma_f32 v[130:131], v[12:13], v[128:129], v[126:127]
	ds_read_b128 v[126:129], v100
	s_waitcnt lgkmcnt(0)
	v_pk_fma_f32 v[126:127], v[6:7], v[126:127], v[130:131]
	s_nop 0
	v_pk_fma_f32 v[130:131], v[8:9], v[128:129], v[126:127]
	ds_read_b128 v[126:129], v101
	s_waitcnt lgkmcnt(0)
	v_pk_fma_f32 v[126:127], v[2:3], v[126:127], v[130:131]
	s_nop 0
	v_pk_fma_f32 v[126:127], v[4:5], v[128:129], v[126:127]
	s_nop 0
	v_add_f32_e32 v125, v126, v127
	ds_read_b128 v[126:129], v102
	s_waitcnt lgkmcnt(0)
	v_pk_fma_f32 v[126:127], v[36:37], v[126:127], 0 op_sel_hi:[1,1,0]
	s_nop 0
	v_pk_fma_f32 v[130:131], v[34:35], v[128:129], v[126:127]
	ds_read_b128 v[126:129], v103
	s_waitcnt lgkmcnt(0)
	v_pk_fma_f32 v[126:127], v[40:41], v[126:127], v[130:131]
	s_nop 0
	v_pk_fma_f32 v[130:131], v[38:39], v[128:129], v[126:127]
	ds_read_b128 v[126:129], v104
	s_waitcnt lgkmcnt(0)
	v_pk_fma_f32 v[126:127], v[22:23], v[126:127], v[130:131]
	s_nop 0
	v_pk_fma_f32 v[130:131], v[24:25], v[128:129], v[126:127]
	ds_read_b128 v[126:129], v105
	s_waitcnt lgkmcnt(0)
	v_pk_fma_f32 v[126:127], v[18:19], v[126:127], v[130:131]
	s_nop 0
	v_pk_fma_f32 v[130:131], v[20:21], v[128:129], v[126:127]
	ds_read_b128 v[126:129], v106
	s_waitcnt lgkmcnt(0)
	v_pk_fma_f32 v[126:127], v[14:15], v[126:127], v[130:131]
	s_nop 0
	v_pk_fma_f32 v[130:131], v[16:17], v[128:129], v[126:127]
	ds_read_b128 v[126:129], v107
	s_waitcnt lgkmcnt(0)
	v_pk_fma_f32 v[126:127], v[10:11], v[126:127], v[130:131]
	s_nop 0
	v_pk_fma_f32 v[130:131], v[12:13], v[128:129], v[126:127]
	ds_read_b128 v[126:129], v108
	s_waitcnt lgkmcnt(0)
	v_pk_fma_f32 v[126:127], v[6:7], v[126:127], v[130:131]
	s_nop 0
	v_pk_fma_f32 v[130:131], v[8:9], v[128:129], v[126:127]
	ds_read_b128 v[126:129], v109
	s_waitcnt lgkmcnt(0)
	v_pk_fma_f32 v[126:127], v[2:3], v[126:127], v[130:131]
	s_nop 0
	v_pk_fma_f32 v[126:127], v[4:5], v[128:129], v[126:127]
	ds_read_b128 v[128:131], v110
	v_add_f32_e32 v126, v126, v127
	s_waitcnt lgkmcnt(0)
	v_pk_fma_f32 v[36:37], v[36:37], v[128:129], 0 op_sel_hi:[1,1,0]
	s_nop 0
	v_pk_fma_f32 v[128:129], v[34:35], v[130:131], v[36:37]
	ds_read_b128 v[34:37], v111
	s_waitcnt lgkmcnt(0)
	v_pk_fma_f32 v[34:35], v[40:41], v[34:35], v[128:129]
	s_nop 0
	v_pk_fma_f32 v[38:39], v[38:39], v[36:37], v[34:35]
	ds_read_b128 v[34:37], v112
	s_waitcnt lgkmcnt(0)
	v_pk_fma_f32 v[22:23], v[22:23], v[34:35], v[38:39]
	s_nop 0
	v_pk_fma_f32 v[34:35], v[24:25], v[36:37], v[22:23]
	ds_read_b128 v[22:25], v113
	s_waitcnt lgkmcnt(0)
	v_pk_fma_f32 v[18:19], v[18:19], v[22:23], v[34:35]
	s_nop 0
	v_pk_fma_f32 v[22:23], v[20:21], v[24:25], v[18:19]
	ds_read_b128 v[18:21], v114
	s_waitcnt lgkmcnt(0)
	v_pk_fma_f32 v[14:15], v[14:15], v[18:19], v[22:23]
	s_nop 0
	v_pk_fma_f32 v[18:19], v[16:17], v[20:21], v[14:15]
	ds_read_b128 v[14:17], v115
	s_waitcnt lgkmcnt(0)
	v_pk_fma_f32 v[10:11], v[10:11], v[14:15], v[18:19]
	s_nop 0
	v_pk_fma_f32 v[14:15], v[12:13], v[16:17], v[10:11]
	ds_read_b128 v[10:13], v116
	s_waitcnt lgkmcnt(0)
	v_pk_fma_f32 v[6:7], v[6:7], v[10:11], v[14:15]
	s_nop 0
	v_pk_fma_f32 v[10:11], v[8:9], v[12:13], v[6:7]
	ds_read_b128 v[6:9], v117
	v_cndmask_b32_e64 v12, v48, v126, s[8:9]
	s_waitcnt lgkmcnt(0)
	v_pk_fma_f32 v[2:3], v[2:3], v[6:7], v[10:11]
	s_nop 0
	v_pk_fma_f32 v[2:3], v[4:5], v[8:9], v[2:3]
	v_xor_b32_e32 v4, 32, v118
	v_add_f32_e32 v3, v2, v3
	v_and_b32_e32 v2, 64, v118
	v_add_u32_e32 v2, 64, v2
	v_cmp_lt_i32_e32 vcc, v4, v2
	v_cndmask_b32_e64 v6, v42, v120, s[8:9]
	v_cndmask_b32_e64 v7, v43, v121, s[8:9]
	v_cndmask_b32_e32 v4, v118, v4, vcc
	v_lshlrev_b32_e32 v4, 2, v4
	ds_bpermute_b32 v6, v4, v6
	ds_bpermute_b32 v7, v4, v7
	v_cndmask_b32_e64 v8, v44, v122, s[8:9]
	ds_bpermute_b32 v8, v4, v8
	v_cndmask_b32_e64 v9, v45, v123, s[8:9]
	ds_bpermute_b32 v9, v4, v9
	v_cndmask_b32_e64 v10, v46, v124, s[8:9]
	v_cndmask_b32_e64 v5, v120, v42, s[8:9]
	ds_bpermute_b32 v10, v4, v10
	v_cndmask_b32_e64 v11, v47, v125, s[8:9]
	s_waitcnt lgkmcnt(4)
	v_add_f32_e32 v5, v5, v6
	v_cndmask_b32_e64 v6, v121, v43, s[8:9]
	ds_bpermute_b32 v11, v4, v11
	s_waitcnt lgkmcnt(4)
	v_add_f32_e32 v6, v6, v7
	v_cndmask_b32_e64 v7, v122, v44, s[8:9]
	ds_bpermute_b32 v12, v4, v12
	s_waitcnt lgkmcnt(4)
	v_add_f32_e32 v7, v7, v8
	v_cndmask_b32_e64 v8, v123, v45, s[8:9]
	s_waitcnt lgkmcnt(3)
	v_add_f32_e32 v8, v8, v9
	v_cndmask_b32_e64 v9, v124, v46, s[8:9]
	s_waitcnt lgkmcnt(2)
	v_add_f32_e32 v9, v9, v10
	v_cndmask_b32_e64 v10, v125, v47, s[8:9]
	s_waitcnt lgkmcnt(1)
	v_add_f32_e32 v10, v10, v11
	v_cndmask_b32_e64 v11, v126, v48, s[8:9]
	s_waitcnt lgkmcnt(0)
	v_add_f32_e32 v11, v11, v12
	v_cndmask_b32_e64 v12, v3, v49, s[8:9]
	v_cndmask_b32_e64 v3, v49, v3, s[8:9]
	ds_bpermute_b32 v3, v4, v3
	v_xor_b32_e32 v4, 16, v118
	v_cmp_lt_i32_e32 vcc, v4, v2
	s_waitcnt lgkmcnt(0)
	v_add_f32_e32 v3, v12, v3
	v_cndmask_b32_e32 v4, v118, v4, vcc
	v_lshlrev_b32_e32 v4, 2, v4
	v_cndmask_b32_e64 v12, v9, v5, s[10:11]
	v_cndmask_b32_e64 v5, v5, v9, s[10:11]
	v_cndmask_b32_e64 v9, v10, v6, s[10:11]
	v_cndmask_b32_e64 v6, v6, v10, s[10:11]
	ds_bpermute_b32 v6, v4, v6
	ds_bpermute_b32 v5, v4, v5
	s_waitcnt lgkmcnt(1)
	v_add_f32_e32 v6, v9, v6
	v_cndmask_b32_e64 v9, v11, v7, s[10:11]
	v_cndmask_b32_e64 v7, v7, v11, s[10:11]
	ds_bpermute_b32 v7, v4, v7
	s_waitcnt lgkmcnt(1)
	v_add_f32_e32 v5, v12, v5
	s_waitcnt lgkmcnt(0)
	v_add_f32_e32 v7, v9, v7
	v_cndmask_b32_e64 v9, v3, v8, s[10:11]
	v_cndmask_b32_e64 v3, v8, v3, s[10:11]
	ds_bpermute_b32 v3, v4, v3
	v_xor_b32_e32 v4, 8, v118
	v_cmp_lt_i32_e32 vcc, v4, v2
	v_cndmask_b32_e64 v8, v7, v5, s[12:13]
	v_cndmask_b32_e64 v5, v5, v7, s[12:13]
	s_waitcnt lgkmcnt(0)
	v_add_f32_e32 v3, v9, v3
	v_cndmask_b32_e32 v4, v118, v4, vcc
	v_lshlrev_b32_e32 v4, 2, v4
	v_cndmask_b32_e64 v7, v3, v6, s[12:13]
	v_cndmask_b32_e64 v3, v6, v3, s[12:13]
	ds_bpermute_b32 v5, v4, v5
	ds_bpermute_b32 v3, v4, v3
	s_waitcnt lgkmcnt(1)
	v_add_f32_e32 v5, v8, v5
	s_waitcnt lgkmcnt(0)
	v_add_f32_e32 v3, v7, v3
	v_cndmask_b32_e64 v4, v3, v5, s[14:15]
	v_cndmask_b32_e64 v3, v5, v3, s[14:15]
	v_xor_b32_e32 v5, 4, v118
	v_cmp_lt_i32_e32 vcc, v5, v2
	s_nop 1
	v_cndmask_b32_e32 v5, v118, v5, vcc
	v_lshlrev_b32_e32 v5, 2, v5
	ds_bpermute_b32 v3, v5, v3
	s_waitcnt lgkmcnt(0)
	v_add_f32_e32 v3, v4, v3
	v_xor_b32_e32 v4, 2, v118
	v_cmp_lt_i32_e32 vcc, v4, v2
	s_nop 1
	v_cndmask_b32_e32 v4, v118, v4, vcc
	v_lshlrev_b32_e32 v4, 2, v4
	ds_bpermute_b32 v4, v4, v3
	s_waitcnt lgkmcnt(0)
	v_add_f32_e32 v3, v3, v4
	v_xor_b32_e32 v4, 1, v118
	v_cmp_lt_i32_e32 vcc, v4, v2
	s_nop 1
	v_cndmask_b32_e32 v2, v118, v4, vcc
	v_lshlrev_b32_e32 v2, 2, v2
	ds_bpermute_b32 v2, v2, v3
	s_and_saveexec_b64 s[30:31], s[16:17]
	s_cbranch_execz .LBB0_94
	s_load_dwordx2 s[34:35], s[6:7], 0x68
	s_waitcnt lgkmcnt(0)
	v_add_f32_e32 v2, v3, v2
	global_load_dword v4, v84, s[34:35]
	s_lshl_b64 s[34:35], s[20:21], 5
	s_waitcnt vmcnt(0)
	v_add_f32_e32 v4, v2, v4
	s_and_saveexec_b64 s[20:21], s[18:19]
	s_xor_b64 s[36:37], exec, s[20:21]
	s_cbranch_execz .LBB0_100
	v_mul_f32_e64 v2, |v4|, s49
	v_exp_f32_e32 v5, v2
	v_max_f32_e32 v4, v4, v4
	v_lshl_add_u64 v[2:3], v[26:27], 0, s[34:35]
	v_min_f32_e32 v4, 0, v4
	v_add_f32_e32 v5, 1.0, v5
	v_cmp_gt_f32_e32 vcc, s50, v5
	v_lshl_add_u64 v[2:3], v[2:3], 0, s[28:29]
	s_nop 0
	v_cndmask_b32_e64 v6, 0, 32, vcc
	v_ldexp_f32 v5, v5, v6
	v_log_f32_e32 v5, v5
	s_nop 0
	v_mul_f32_e32 v6, 0x3f317217, v5
	v_fma_f32 v6, v5, s51, -v6
	v_fmac_f32_e32 v6, 0x3377d1cf, v5
	v_fmac_f32_e32 v6, 0x3f317217, v5
	v_cmp_lt_f32_e64 s[20:21], |v5|, s52
	s_nop 1
	v_cndmask_b32_e64 v5, v5, v6, s[20:21]
	v_cndmask_b32_e32 v6, 0, v119, vcc
	v_sub_f32_e32 v5, v5, v6
	v_sub_f32_e32 v4, v4, v5
